# GEMM K-loops: leading half retires its LDS-DMA loads at the end of the following MFMA segment (one more interval), trailing half keeps the early wait; plus earlier edits
# baseline (speedup 1.0000x reference)
; #define PG8_STAGE(bufoff, gbase, voff) do { _Pragma("unroll") for (int _i = 0; _i < 2; ++_i) \
;         __builtin_amdgcn_global_load_lds((const unsigned*)((const char*)(gbase) + (voff)[_i]), (PG8_LAS unsigned*)(lds + (bufoff) + ldsw + _i * 8192), 16, 0, 0); } while (0)
; #define PG8_LDA(dst, b, h) do { _Pragma("unroll") for (int m = 0; m < 4; ++m) _Pragma("unroll") for (int k = 0; k < 2; ++k) dst[m][k] = *(const PG8_LAS bf16x8*)(lds + PG8_SA(b, h) + aoff + m * 2048 + k * 1024); } while (0)
; #define PG8_LDB(dst, b, h) do { _Pragma("unroll") for (int n = 0; n < 2; ++n) _Pragma("unroll") for (int k = 0; k < 2; ++k) dst[n][k] = *(const PG8_LAS bf16x8*)(lds + PG8_SB(b, h) + boff + n * 2048 + k * 1024); } while (0)
; #define PG8_MMA(ai, bj, At, Bt) do { __builtin_amdgcn_s_setprio(1); _Pragma("unroll") for (int m = 0; m < 4; ++m) _Pragma("unroll") for (int n = 0; n < 2; ++n) _Pragma("unroll") for (int k = 0; k < 2; ++k) \
;         acc[ai][bj][m][n] = __builtin_amdgcn_mfma_f32_16x16x32_bf16(Bt[n][k], At[m][k], acc[ai][bj][m][n], 0, 0, 0); __builtin_amdgcn_s_setprio(0); } while (0)
; template <class Epi, class Sched, bool ALIGN_EPI = false, bool SP2 = false>
; __device__ __forceinline__ void gemm_phase(PG8_LAS unsigned char* lds, const Gemm g, const Sched& S, const Epi& E, volatile PG8_LAS unsigned* sw = nullptr) {
;     ...
;             PG8_LDB(B0, 0, 0); PG8_LDB(B1, 0, 1); PG8_SCHED; PG8_LDA(At, 0, 0); PG8_STAGE(PG8_SA(1, 1), a1 + hstep, voffA);
;             PG8_WAIT_V(8); PG8_WAIT_L(0); PG8_BAR; PG8_MMA(0, 0, At, B0); PG8_MMA(0, 1, At, B1); PG8_BAR; PG8_SCHED;
;             PG8_LDA(At, 0, 1); PG8_STAGE(PG8_SB(0, 0), b2, voffB); PG8_STAGE(PG8_SB(0, 1), b2 + hstep, voffB); PG8_STAGE(PG8_SA(0, 0), a2, voffA);
;             PG8_WAIT_V(8); PG8_WAIT_L(0); PG8_BAR; PG8_MMA(1, 0, At, B0); PG8_MMA(1, 1, At, B1); PG8_BAR; PG8_SCHED;
;             PG8_LDB(B0, 1, 0); PG8_LDB(B1, 1, 1); PG8_SCHED; PG8_LDA(At, 1, 0); PG8_STAGE(PG8_SA(0, 1), a2 + hstep, voffA);
;             PG8_WAIT_V(8); PG8_WAIT_L(0); PG8_BAR; PG8_MMA(0, 0, At, B0); PG8_MMA(0, 1, At, B1); PG8_BAR; PG8_SCHED;
;             PG8_LDA(At, 1, 1); PG8_STAGE(PG8_SB(1, 0), b3, voffB); PG8_STAGE(PG8_SB(1, 1), b3 + hstep, voffB); PG8_STAGE(PG8_SA(1, 0), a3, voffA);
;             PG8_WAIT_V(8); PG8_WAIT_L(0); PG8_BAR; PG8_MMA(1, 0, At, B0); PG8_MMA(1, 1, At, B1); PG8_BAR; PG8_SCHED;
.LBB0_162:
	ds_read_b128 v[150:153], v146
	ds_read_b128 v[154:157], v146 offset:1024
	ds_read_b128 v[158:161], v146 offset:2048
	ds_read_b128 v[162:165], v146 offset:3072
	ds_read_b128 v[166:169], v147
	ds_read_b128 v[170:173], v147 offset:1024
	ds_read_b128 v[174:177], v147 offset:2048
	ds_read_b128 v[178:181], v147 offset:3072
	s_add_u32 s50, s48, 0x4000
	s_addc_u32 s51, s49, 0
	s_cmp_eq_u32 s65, 12
	s_cselect_b32 s54, s11, s50
	s_cselect_b32 s55, s3, s51
	s_cselect_b32 s52, s47, s59
	s_cselect_b32 s53, s13, s64
	s_add_u32 s50, s54, 0x8000
	s_addc_u32 s51, s55, 0
	v_lshl_add_u64 v[142:143], s[48:49], 0, v[138:139]
	s_add_i32 m0, s20, 0xc000
	ds_read_b128 v[182:185], v148
	ds_read_b128 v[186:189], v148 offset:1024
	ds_read_b128 v[190:193], v148 offset:2048
	ds_read_b128 v[194:197], v148 offset:3072
	ds_read_b128 v[198:201], v148 offset:4096
	ds_read_b128 v[202:205], v148 offset:5120
	ds_read_b128 v[206:209], v148 offset:6144
	ds_read_b128 v[210:213], v148 offset:7168
	global_load_lds_dwordx4 v[142:143], off
	v_lshl_add_u64 v[142:143], s[48:49], 0, v[140:141]
	s_add_i32 m0, s20, 0xe000
	s_nop 0
	global_load_lds_dwordx4 v[142:143], off
	s_and_b64 vcc, exec, s[6:7]
	s_cbranch_vccnz .Ldw_162_0
	s_waitcnt vmcnt(8)
.Ldw_162_0:
	s_waitcnt lgkmcnt(0)
	s_barrier
	s_setprio 1
	s_waitcnt lgkmcnt(0)
	v_mfma_f32_16x16x32_bf16 v[126:129], v[150:153], v[182:185], v[126:129]
	v_mfma_f32_16x16x32_bf16 v[122:125], v[158:161], v[182:185], v[122:125]
	v_mfma_f32_16x16x32_bf16 v[118:121], v[150:153], v[190:193], v[118:121]
	v_mfma_f32_16x16x32_bf16 v[110:113], v[158:161], v[190:193], v[110:113]
	v_mfma_f32_16x16x32_bf16 v[102:105], v[150:153], v[198:201], v[102:105]
	v_mfma_f32_16x16x32_bf16 v[94:97], v[158:161], v[198:201], v[94:97]
	v_mfma_f32_16x16x32_bf16 v[86:89], v[150:153], v[206:209], v[86:89]
	v_mfma_f32_16x16x32_bf16 v[78:81], v[158:161], v[206:209], v[78:81]
	v_mfma_f32_16x16x32_bf16 v[126:129], v[154:157], v[186:189], v[126:129]
	v_mfma_f32_16x16x32_bf16 v[122:125], v[162:165], v[186:189], v[122:125]
	v_mfma_f32_16x16x32_bf16 v[118:121], v[154:157], v[194:197], v[118:121]
	v_mfma_f32_16x16x32_bf16 v[110:113], v[162:165], v[194:197], v[110:113]
	v_mfma_f32_16x16x32_bf16 v[102:105], v[154:157], v[202:205], v[102:105]
	v_mfma_f32_16x16x32_bf16 v[94:97], v[162:165], v[202:205], v[94:97]
	v_mfma_f32_16x16x32_bf16 v[86:89], v[154:157], v[210:213], v[86:89]
	v_mfma_f32_16x16x32_bf16 v[78:81], v[162:165], v[210:213], v[78:81]
	s_setprio 0
	s_setprio 1
	v_mfma_f32_16x16x32_bf16 v[114:117], v[166:169], v[182:185], v[114:117]
	v_mfma_f32_16x16x32_bf16 v[106:109], v[174:177], v[182:185], v[106:109]
	v_mfma_f32_16x16x32_bf16 v[98:101], v[166:169], v[190:193], v[98:101]
	v_mfma_f32_16x16x32_bf16 v[90:93], v[174:177], v[190:193], v[90:93]
	v_mfma_f32_16x16x32_bf16 v[82:85], v[166:169], v[198:201], v[82:85]
	v_mfma_f32_16x16x32_bf16 v[74:77], v[174:177], v[198:201], v[74:77]
	v_mfma_f32_16x16x32_bf16 v[70:73], v[166:169], v[206:209], v[70:73]
	v_mfma_f32_16x16x32_bf16 v[66:69], v[174:177], v[206:209], v[66:69]
	v_mfma_f32_16x16x32_bf16 v[114:117], v[170:173], v[186:189], v[114:117]
	v_mfma_f32_16x16x32_bf16 v[106:109], v[178:181], v[186:189], v[106:109]
	v_mfma_f32_16x16x32_bf16 v[98:101], v[170:173], v[194:197], v[98:101]
	v_mfma_f32_16x16x32_bf16 v[90:93], v[178:181], v[194:197], v[90:93]
	v_mfma_f32_16x16x32_bf16 v[82:85], v[170:173], v[202:205], v[82:85]
	v_mfma_f32_16x16x32_bf16 v[74:77], v[178:181], v[202:205], v[74:77]
	v_mfma_f32_16x16x32_bf16 v[70:73], v[170:173], v[210:213], v[70:73]
	v_mfma_f32_16x16x32_bf16 v[66:69], v[178:181], v[210:213], v[66:69]
	s_setprio 0
	s_waitcnt vmcnt(8)
	s_barrier
	s_add_i32 s70, s57, s19
	v_lshl_add_u64 v[142:143], s[52:53], 0, v[134:135]
	s_mov_b32 m0, s70
	ds_read_b128 v[182:185], v148 offset:16384
	ds_read_b128 v[186:189], v148 offset:17408
	ds_read_b128 v[190:193], v148 offset:18432
	ds_read_b128 v[194:197], v148 offset:19456
	ds_read_b128 v[198:201], v148 offset:20480
	ds_read_b128 v[202:205], v148 offset:21504
	ds_read_b128 v[206:209], v148 offset:22528
	ds_read_b128 v[210:213], v148 offset:23552
	global_load_lds_dwordx4 v[142:143], off
	s_add_i32 m0, s70, 0x2000
	s_add_u32 s70, s52, 0x4000
	v_lshl_add_u64 v[142:143], s[52:53], 0, v[130:131]
	s_addc_u32 s71, s53, 0
	s_add_i32 s72, s58, s19
	global_load_lds_dwordx4 v[142:143], off
	v_lshl_add_u64 v[142:143], s[70:71], 0, v[134:135]
	s_mov_b32 m0, s72
	s_nop 0
	global_load_lds_dwordx4 v[142:143], off
	v_lshl_add_u64 v[142:143], s[70:71], 0, v[130:131]
	s_add_i32 m0, s72, 0x2000
	s_nop 0
	global_load_lds_dwordx4 v[142:143], off
	v_lshl_add_u64 v[142:143], s[54:55], 0, v[136:137]
	s_mov_b32 m0, s20
	s_nop 0
	global_load_lds_dwordx4 v[142:143], off
	v_lshl_add_u64 v[142:143], s[54:55], 0, v[132:133]
	s_mov_b32 m0, s21
	s_nop 0
	global_load_lds_dwordx4 v[142:143], off
	s_and_b64 vcc, exec, s[6:7]
	s_cbranch_vccnz .Ldw_162_1
	s_waitcnt vmcnt(8)
; #define PG8_STAGE(bufoff, gbase, voff) do { _Pragma("unroll") for (int _i = 0; _i < 2; ++_i) \
;         __builtin_amdgcn_global_load_lds((const unsigned*)((const char*)(gbase) + (voff)[_i]), (PG8_LAS unsigned*)(lds + (bufoff) + ldsw + _i * 8192), 16, 0, 0); } while (0)
; #define PG8_LDA(dst, b, h) do { _Pragma("unroll") for (int m = 0; m < 4; ++m) _Pragma("unroll") for (int k = 0; k < 2; ++k) dst[m][k] = *(const PG8_LAS bf16x8*)(lds + PG8_SA(b, h) + aoff + m * 2048 + k * 1024); } while (0)
; #define PG8_LDB(dst, b, h) do { _Pragma("unroll") for (int n = 0; n < 2; ++n) _Pragma("unroll") for (int k = 0; k < 2; ++k) dst[n][k] = *(const PG8_LAS bf16x8*)(lds + PG8_SB(b, h) + boff + n * 2048 + k * 1024); } while (0)
; #define PG8_MMA(ai, bj, At, Bt) do { __builtin_amdgcn_s_setprio(1); _Pragma("unroll") for (int m = 0; m < 4; ++m) _Pragma("unroll") for (int n = 0; n < 2; ++n) _Pragma("unroll") for (int k = 0; k < 2; ++k) \
;         acc[ai][bj][m][n] = __builtin_amdgcn_mfma_f32_16x16x32_bf16(Bt[n][k], At[m][k], acc[ai][bj][m][n], 0, 0, 0); __builtin_amdgcn_s_setprio(0); } while (0)
; #define PG8_WAIT_V(n) asm volatile("s_waitcnt vmcnt(" #n ")" ::: "memory")
; #define PG8_WAIT_L(n) asm volatile("s_waitcnt lgkmcnt(" #n ")" ::: "memory")
; #define PG8_BAR __builtin_amdgcn_s_barrier()
; #define PG8_SCHED __builtin_amdgcn_sched_barrier(0)
; template <class Epi, class Sched, bool ALIGN_EPI = false, bool SP2 = false>
; __device__ __forceinline__ void gemm_phase(PG8_LAS unsigned char* lds, const Gemm g, const Sched& S, const Epi& E, volatile PG8_LAS unsigned* sw = nullptr) {
;     ...
;             PG8_WAIT_V(8); PG8_WAIT_L(0); PG8_BAR; PG8_MMA(1, 0, At, B0); PG8_MMA(1, 1, At, B1); PG8_BAR; PG8_SCHED;
;             PG8_LDB(B0, 1, 0); PG8_LDB(B1, 1, 1); PG8_SCHED; PG8_LDA(At, 1, 0); PG8_STAGE(PG8_SA(0, 1), a2 + hstep, voffA);
;             PG8_WAIT_V(8); PG8_WAIT_L(0); PG8_BAR; PG8_MMA(0, 0, At, B0); PG8_MMA(0, 1, At, B1); PG8_BAR; PG8_SCHED;
.Ldw_162_1:
	s_waitcnt lgkmcnt(0)
	s_barrier
	s_setprio 1
	s_waitcnt lgkmcnt(0)
	v_mfma_f32_16x16x32_bf16 v[62:65], v[150:153], v[182:185], v[62:65]
	v_mfma_f32_16x16x32_bf16 v[58:61], v[158:161], v[182:185], v[58:61]
	v_mfma_f32_16x16x32_bf16 v[54:57], v[150:153], v[190:193], v[54:57]
	v_mfma_f32_16x16x32_bf16 v[46:49], v[158:161], v[190:193], v[46:49]
	v_mfma_f32_16x16x32_bf16 v[38:41], v[150:153], v[198:201], v[38:41]
	v_mfma_f32_16x16x32_bf16 v[30:33], v[158:161], v[198:201], v[30:33]
	v_mfma_f32_16x16x32_bf16 v[22:25], v[150:153], v[206:209], v[22:25]
	v_mfma_f32_16x16x32_bf16 v[14:17], v[158:161], v[206:209], v[14:17]
	v_mfma_f32_16x16x32_bf16 v[62:65], v[154:157], v[186:189], v[62:65]
	v_mfma_f32_16x16x32_bf16 v[58:61], v[162:165], v[186:189], v[58:61]
	v_mfma_f32_16x16x32_bf16 v[54:57], v[154:157], v[194:197], v[54:57]
	v_mfma_f32_16x16x32_bf16 v[46:49], v[162:165], v[194:197], v[46:49]
	v_mfma_f32_16x16x32_bf16 v[38:41], v[154:157], v[202:205], v[38:41]
	v_mfma_f32_16x16x32_bf16 v[30:33], v[162:165], v[202:205], v[30:33]
	v_mfma_f32_16x16x32_bf16 v[22:25], v[154:157], v[210:213], v[22:25]
	v_mfma_f32_16x16x32_bf16 v[14:17], v[162:165], v[210:213], v[14:17]
	s_setprio 0
	s_setprio 1
	v_mfma_f32_16x16x32_bf16 v[50:53], v[166:169], v[182:185], v[50:53]
	v_mfma_f32_16x16x32_bf16 v[42:45], v[174:177], v[182:185], v[42:45]
	v_mfma_f32_16x16x32_bf16 v[34:37], v[166:169], v[190:193], v[34:37]
	v_mfma_f32_16x16x32_bf16 v[26:29], v[174:177], v[190:193], v[26:29]
	v_mfma_f32_16x16x32_bf16 v[18:21], v[166:169], v[198:201], v[18:21]
	v_mfma_f32_16x16x32_bf16 v[10:13], v[174:177], v[198:201], v[10:13]
	v_mfma_f32_16x16x32_bf16 v[6:9], v[166:169], v[206:209], v[6:9]
	v_mfma_f32_16x16x32_bf16 v[2:5], v[174:177], v[206:209], v[2:5]
	v_mfma_f32_16x16x32_bf16 v[50:53], v[170:173], v[186:189], v[50:53]
	v_mfma_f32_16x16x32_bf16 v[42:45], v[178:181], v[186:189], v[42:45]
	v_mfma_f32_16x16x32_bf16 v[34:37], v[170:173], v[194:197], v[34:37]
	v_mfma_f32_16x16x32_bf16 v[26:29], v[178:181], v[194:197], v[26:29]
	v_mfma_f32_16x16x32_bf16 v[18:21], v[170:173], v[202:205], v[18:21]
	v_mfma_f32_16x16x32_bf16 v[10:13], v[178:181], v[202:205], v[10:13]
	v_mfma_f32_16x16x32_bf16 v[6:9], v[170:173], v[210:213], v[6:9]
	v_mfma_f32_16x16x32_bf16 v[2:5], v[178:181], v[210:213], v[2:5]
	s_setprio 0
	s_waitcnt vmcnt(8)
	s_barrier
	s_add_i32 s70, 0, 0x18000
	v_add_u32_e32 v142, s70, v144
	s_add_i32 s71, 0, 0x1c000
	ds_read_b128 v[150:153], v142
	ds_read_b128 v[154:157], v142 offset:1024
	ds_read_b128 v[158:161], v142 offset:2048
	ds_read_b128 v[162:165], v142 offset:3072
	v_add_u32_e32 v142, s71, v144
	ds_read_b128 v[166:169], v142
	ds_read_b128 v[170:173], v142 offset:1024
	ds_read_b128 v[174:177], v142 offset:2048
	ds_read_b128 v[178:181], v142 offset:3072
	s_add_u32 s54, s54, 0x4000
	s_addc_u32 s55, s55, 0
	s_mov_b32 m0, s22
	v_lshl_add_u64 v[142:143], s[54:55], 0, v[136:137]
	ds_read_b128 v[182:185], v148 offset:32768
	ds_read_b128 v[186:189], v148 offset:33792
	ds_read_b128 v[190:193], v148 offset:34816
	ds_read_b128 v[194:197], v148 offset:35840
	ds_read_b128 v[198:201], v148 offset:36864
	ds_read_b128 v[202:205], v148 offset:37888
	ds_read_b128 v[206:209], v148 offset:38912
	ds_read_b128 v[210:213], v148 offset:39936
	global_load_lds_dwordx4 v[142:143], off
	v_lshl_add_u64 v[142:143], s[54:55], 0, v[132:133]
	s_mov_b32 m0, s23
	s_nop 0
	global_load_lds_dwordx4 v[142:143], off
	s_and_b64 vcc, exec, s[6:7]
	s_cbranch_vccnz .Ldw_162_2
	s_waitcnt vmcnt(8)
; #define PG8_STAGE(bufoff, gbase, voff) do { _Pragma("unroll") for (int _i = 0; _i < 2; ++_i) \
;         __builtin_amdgcn_global_load_lds((const unsigned*)((const char*)(gbase) + (voff)[_i]), (PG8_LAS unsigned*)(lds + (bufoff) + ldsw + _i * 8192), 16, 0, 0); } while (0)
; template <class Epi, class Sched, bool ALIGN_EPI = false, bool SP2 = false>
; __device__ __forceinline__ void gemm_phase(PG8_LAS unsigned char* lds, const Gemm g, const Sched& S, const Epi& E, volatile PG8_LAS unsigned* sw = nullptr) {
;     ...
;             PG8_LDB(B0, 1, 0); PG8_LDB(B1, 1, 1); PG8_SCHED; PG8_LDA(At, 1, 0); PG8_STAGE(PG8_SA(0, 1), a2 + hstep, voffA);
;             PG8_WAIT_V(8); PG8_WAIT_L(0); PG8_BAR; PG8_MMA(0, 0, At, B0); PG8_MMA(0, 1, At, B1); PG8_BAR; PG8_SCHED;
;             PG8_LDA(At, 1, 1); PG8_STAGE(PG8_SB(1, 0), b3, voffB); PG8_STAGE(PG8_SB(1, 1), b3 + hstep, voffB); PG8_STAGE(PG8_SA(1, 0), a3, voffA);
;             PG8_WAIT_V(8); PG8_WAIT_L(0); PG8_BAR; PG8_MMA(1, 0, At, B0); PG8_MMA(1, 1, At, B1); PG8_BAR; PG8_SCHED;
;             } else {
;             PG8_LDB(B0, 0, 0); PG8_SCHED; PG8_LDA(At, 0, 0); PG8_STAGE(PG8_SA(1, 1), a1 + hstep, voffA);
;             PG8_WAIT_L(8); PG8_BAR; PG8_WAIT_L(0); PG8_MMA(0, 0, At, B0); PG8_BAR; PG8_SCHED;
;             PG8_LDB(B1, 0, 1); PG8_STAGE(PG8_SB(0, 0), b2, voffB);
;             PG8_BAR; PG8_WAIT_L(0); PG8_MMA(0, 1, At, B1); PG8_BAR;
;             PG8_LDA(At, 0, 1); PG8_STAGE(PG8_SA(0, 0), a2, voffA);
;             PG8_BAR; PG8_WAIT_L(0); PG8_MMA(1, 0, At, B0); PG8_BAR; PG8_SCHED;
;             PG8_STAGE(PG8_SB(0, 1), b2 + hstep, voffB);
;             PG8_WAIT_V(6); PG8_BAR; PG8_MMA(1, 1, At, B1); PG8_BAR;
;             PG8_LDB(B0, 1, 0); PG8_SCHED; PG8_LDA(At, 1, 0); PG8_STAGE(PG8_SA(0, 1), a2 + hstep, voffA);
;             PG8_WAIT_L(8); PG8_BAR; PG8_WAIT_L(0); PG8_MMA(0, 0, At, B0); PG8_BAR; PG8_SCHED;
;             PG8_LDB(B1, 1, 1); PG8_STAGE(PG8_SB(1, 0), b3, voffB);
;             PG8_BAR; PG8_WAIT_L(0); PG8_MMA(0, 1, At, B1); PG8_BAR;
;             PG8_LDA(At, 1, 1); PG8_STAGE(PG8_SA(1, 0), a3, voffA);
;             PG8_BAR; PG8_WAIT_L(0); PG8_MMA(1, 0, At, B0); PG8_BAR; PG8_SCHED;
;             PG8_STAGE(PG8_SB(1, 1), b3 + hstep, voffB);
;             PG8_WAIT_V(6); PG8_BAR; PG8_MMA(1, 1, At, B1); PG8_BAR;
;             }
;         }
;         if constexpr (ALIGN_EPI) { if (wr == 0) PG8_BAR; }
.Ldw_162_2:
	s_waitcnt lgkmcnt(0)
	s_barrier
	s_setprio 1
	s_waitcnt lgkmcnt(0)
	v_mfma_f32_16x16x32_bf16 v[126:129], v[150:153], v[182:185], v[126:129]
	v_mfma_f32_16x16x32_bf16 v[122:125], v[158:161], v[182:185], v[122:125]
	v_mfma_f32_16x16x32_bf16 v[118:121], v[150:153], v[190:193], v[118:121]
	v_mfma_f32_16x16x32_bf16 v[110:113], v[158:161], v[190:193], v[110:113]
	v_mfma_f32_16x16x32_bf16 v[102:105], v[150:153], v[198:201], v[102:105]
	v_mfma_f32_16x16x32_bf16 v[94:97], v[158:161], v[198:201], v[94:97]
	v_mfma_f32_16x16x32_bf16 v[86:89], v[150:153], v[206:209], v[86:89]
	v_mfma_f32_16x16x32_bf16 v[78:81], v[158:161], v[206:209], v[78:81]
	v_mfma_f32_16x16x32_bf16 v[126:129], v[154:157], v[186:189], v[126:129]
	v_mfma_f32_16x16x32_bf16 v[122:125], v[162:165], v[186:189], v[122:125]
	v_mfma_f32_16x16x32_bf16 v[118:121], v[154:157], v[194:197], v[118:121]
	v_mfma_f32_16x16x32_bf16 v[110:113], v[162:165], v[194:197], v[110:113]
	v_mfma_f32_16x16x32_bf16 v[102:105], v[154:157], v[202:205], v[102:105]
	v_mfma_f32_16x16x32_bf16 v[94:97], v[162:165], v[202:205], v[94:97]
	v_mfma_f32_16x16x32_bf16 v[86:89], v[154:157], v[210:213], v[86:89]
	v_mfma_f32_16x16x32_bf16 v[78:81], v[162:165], v[210:213], v[78:81]
	s_setprio 0
	s_setprio 1
	v_mfma_f32_16x16x32_bf16 v[114:117], v[166:169], v[182:185], v[114:117]
	v_mfma_f32_16x16x32_bf16 v[106:109], v[174:177], v[182:185], v[106:109]
	v_mfma_f32_16x16x32_bf16 v[98:101], v[166:169], v[190:193], v[98:101]
	v_mfma_f32_16x16x32_bf16 v[90:93], v[174:177], v[190:193], v[90:93]
	v_mfma_f32_16x16x32_bf16 v[82:85], v[166:169], v[198:201], v[82:85]
	v_mfma_f32_16x16x32_bf16 v[74:77], v[174:177], v[198:201], v[74:77]
	v_mfma_f32_16x16x32_bf16 v[70:73], v[166:169], v[206:209], v[70:73]
	v_mfma_f32_16x16x32_bf16 v[66:69], v[174:177], v[206:209], v[66:69]
	v_mfma_f32_16x16x32_bf16 v[114:117], v[170:173], v[186:189], v[114:117]
	v_mfma_f32_16x16x32_bf16 v[106:109], v[178:181], v[186:189], v[106:109]
	v_mfma_f32_16x16x32_bf16 v[98:101], v[170:173], v[194:197], v[98:101]
	v_mfma_f32_16x16x32_bf16 v[90:93], v[178:181], v[194:197], v[90:93]
	v_mfma_f32_16x16x32_bf16 v[82:85], v[170:173], v[202:205], v[82:85]
	v_mfma_f32_16x16x32_bf16 v[74:77], v[178:181], v[202:205], v[74:77]
	v_mfma_f32_16x16x32_bf16 v[70:73], v[170:173], v[210:213], v[70:73]
	v_mfma_f32_16x16x32_bf16 v[66:69], v[178:181], v[210:213], v[66:69]
	s_setprio 0
	s_waitcnt vmcnt(8)
	s_barrier
	s_add_u32 s54, s52, 0x8000
	s_addc_u32 s55, s53, 0
	s_add_i32 s70, s70, s19
	v_lshl_add_u64 v[142:143], s[54:55], 0, v[134:135]
	s_mov_b32 m0, s70
	ds_read_b128 v[182:185], v148 offset:49152
	ds_read_b128 v[186:189], v148 offset:50176
	ds_read_b128 v[190:193], v148 offset:51200
	ds_read_b128 v[194:197], v148 offset:52224
	ds_read_b128 v[198:201], v148 offset:53248
	ds_read_b128 v[202:205], v148 offset:54272
	ds_read_b128 v[206:209], v148 offset:55296
	ds_read_b128 v[210:213], v148 offset:56320
	global_load_lds_dwordx4 v[142:143], off
	s_add_i32 m0, s70, 0x2000
	s_add_u32 s52, s52, 0xc000
	v_lshl_add_u64 v[142:143], s[54:55], 0, v[130:131]
	s_addc_u32 s53, s53, 0
	s_add_i32 s54, s71, s19
	global_load_lds_dwordx4 v[142:143], off
	v_lshl_add_u64 v[142:143], s[52:53], 0, v[134:135]
	s_mov_b32 m0, s54
	s_nop 0
	global_load_lds_dwordx4 v[142:143], off
	v_lshl_add_u64 v[142:143], s[52:53], 0, v[130:131]
	s_add_i32 m0, s54, 0x2000
	s_nop 0
	global_load_lds_dwordx4 v[142:143], off
	v_lshl_add_u64 v[142:143], s[50:51], 0, v[136:137]
	s_mov_b32 m0, s41
	s_nop 0
	global_load_lds_dwordx4 v[142:143], off
	v_lshl_add_u64 v[142:143], s[50:51], 0, v[132:133]
	s_mov_b32 m0, s42
	s_nop 0
	global_load_lds_dwordx4 v[142:143], off
	s_and_b64 vcc, exec, s[6:7]
	s_cbranch_vccnz .Ldw_162_3
	s_waitcnt vmcnt(8)
.Ldw_162_3:
	s_waitcnt lgkmcnt(0)
	s_barrier
	s_setprio 1
	s_waitcnt lgkmcnt(0)
	v_mfma_f32_16x16x32_bf16 v[62:65], v[150:153], v[182:185], v[62:65]
	v_mfma_f32_16x16x32_bf16 v[58:61], v[158:161], v[182:185], v[58:61]
	v_mfma_f32_16x16x32_bf16 v[54:57], v[150:153], v[190:193], v[54:57]
	v_mfma_f32_16x16x32_bf16 v[46:49], v[158:161], v[190:193], v[46:49]
	v_mfma_f32_16x16x32_bf16 v[38:41], v[150:153], v[198:201], v[38:41]
	v_mfma_f32_16x16x32_bf16 v[30:33], v[158:161], v[198:201], v[30:33]
	v_mfma_f32_16x16x32_bf16 v[22:25], v[150:153], v[206:209], v[22:25]
	v_mfma_f32_16x16x32_bf16 v[14:17], v[158:161], v[206:209], v[14:17]
	v_mfma_f32_16x16x32_bf16 v[62:65], v[154:157], v[186:189], v[62:65]
	v_mfma_f32_16x16x32_bf16 v[58:61], v[162:165], v[186:189], v[58:61]
	v_mfma_f32_16x16x32_bf16 v[54:57], v[154:157], v[194:197], v[54:57]
	v_mfma_f32_16x16x32_bf16 v[46:49], v[162:165], v[194:197], v[46:49]
	v_mfma_f32_16x16x32_bf16 v[38:41], v[154:157], v[202:205], v[38:41]
	v_mfma_f32_16x16x32_bf16 v[30:33], v[162:165], v[202:205], v[30:33]
	v_mfma_f32_16x16x32_bf16 v[22:25], v[154:157], v[210:213], v[22:25]
	v_mfma_f32_16x16x32_bf16 v[14:17], v[162:165], v[210:213], v[14:17]
	s_setprio 0
	s_setprio 1
	v_mfma_f32_16x16x32_bf16 v[50:53], v[166:169], v[182:185], v[50:53]
	v_mfma_f32_16x16x32_bf16 v[42:45], v[174:177], v[182:185], v[42:45]
	v_mfma_f32_16x16x32_bf16 v[34:37], v[166:169], v[190:193], v[34:37]
	v_mfma_f32_16x16x32_bf16 v[26:29], v[174:177], v[190:193], v[26:29]
	v_mfma_f32_16x16x32_bf16 v[18:21], v[166:169], v[198:201], v[18:21]
	v_mfma_f32_16x16x32_bf16 v[10:13], v[174:177], v[198:201], v[10:13]
	v_mfma_f32_16x16x32_bf16 v[6:9], v[166:169], v[206:209], v[6:9]
	v_mfma_f32_16x16x32_bf16 v[2:5], v[174:177], v[206:209], v[2:5]
	v_mfma_f32_16x16x32_bf16 v[50:53], v[170:173], v[186:189], v[50:53]
	v_mfma_f32_16x16x32_bf16 v[42:45], v[178:181], v[186:189], v[42:45]
	v_mfma_f32_16x16x32_bf16 v[34:37], v[170:173], v[194:197], v[34:37]
	v_mfma_f32_16x16x32_bf16 v[26:29], v[178:181], v[194:197], v[26:29]
	v_mfma_f32_16x16x32_bf16 v[18:21], v[170:173], v[202:205], v[18:21]
	v_mfma_f32_16x16x32_bf16 v[10:13], v[178:181], v[202:205], v[10:13]
	v_mfma_f32_16x16x32_bf16 v[6:9], v[170:173], v[210:213], v[6:9]
	v_mfma_f32_16x16x32_bf16 v[2:5], v[178:181], v[210:213], v[2:5]
	s_setprio 0
	s_waitcnt vmcnt(8)
	s_barrier
	s_add_i32 s65, s65, 2
	s_add_u32 s48, s48, 0x10000
	s_addc_u32 s49, s49, 0
	s_add_u32 s59, s59, 0x10000
	s_addc_u32 s64, s64, 0
	s_cmp_gt_u32 s65, 13
	s_cbranch_scc0 .LBB0_162
	s_and_b64 vcc, exec, s[6:7]
	s_cbranch_vccz .LBB0_165
	s_barrier

; #define PG8_STAGE(bufoff, gbase, voff) do { _Pragma("unroll") for (int _i = 0; _i < 2; ++_i) \
;         __builtin_amdgcn_global_load_lds((const unsigned*)((const char*)(gbase) + (voff)[_i]), (PG8_LAS unsigned*)(lds + (bufoff) + ldsw + _i * 8192), 16, 0, 0); } while (0)
; #define PG8_LDA(dst, b, h) do { _Pragma("unroll") for (int m = 0; m < 4; ++m) _Pragma("unroll") for (int k = 0; k < 2; ++k) dst[m][k] = *(const PG8_LAS bf16x8*)(lds + PG8_SA(b, h) + aoff + m * 2048 + k * 1024); } while (0)
; #define PG8_LDB(dst, b, h) do { _Pragma("unroll") for (int n = 0; n < 2; ++n) _Pragma("unroll") for (int k = 0; k < 2; ++k) dst[n][k] = *(const PG8_LAS bf16x8*)(lds + PG8_SB(b, h) + boff + n * 2048 + k * 1024); } while (0)
; #define PG8_MMA(ai, bj, At, Bt) do { __builtin_amdgcn_s_setprio(1); _Pragma("unroll") for (int m = 0; m < 4; ++m) _Pragma("unroll") for (int n = 0; n < 2; ++n) _Pragma("unroll") for (int k = 0; k < 2; ++k) \
;         acc[ai][bj][m][n] = __builtin_amdgcn_mfma_f32_16x16x32_bf16(Bt[n][k], At[m][k], acc[ai][bj][m][n], 0, 0, 0); __builtin_amdgcn_s_setprio(0); } while (0)
; #define PG8_WAIT_V(n) asm volatile("s_waitcnt vmcnt(" #n ")" ::: "memory")
; #define PG8_WAIT_L(n) asm volatile("s_waitcnt lgkmcnt(" #n ")" ::: "memory")
; #define PG8_BAR __builtin_amdgcn_s_barrier()
; #define PG8_SCHED __builtin_amdgcn_sched_barrier(0)
; template <class Epi, class Sched, bool ALIGN_EPI = false, bool SP2 = false>
; __device__ __forceinline__ void gemm_phase(PG8_LAS unsigned char* lds, const Gemm g, const Sched& S, const Epi& E, volatile PG8_LAS unsigned* sw = nullptr) {
;     ...
;             PG8_LDB(B0, 0, 0); PG8_LDB(B1, 0, 1); PG8_SCHED; PG8_LDA(At, 0, 0); PG8_STAGE(PG8_SA(1, 1), a1 + hstep, voffA);
;             PG8_WAIT_V(8); PG8_WAIT_L(0); PG8_BAR; PG8_MMA(0, 0, At, B0); PG8_MMA(0, 1, At, B1); PG8_BAR; PG8_SCHED;
;             PG8_LDA(At, 0, 1); PG8_STAGE(PG8_SB(0, 0), b2, voffB); PG8_STAGE(PG8_SB(0, 1), b2 + hstep, voffB); PG8_STAGE(PG8_SA(0, 0), a2, voffA);
;             PG8_WAIT_V(8); PG8_WAIT_L(0); PG8_BAR; PG8_MMA(1, 0, At, B0); PG8_MMA(1, 1, At, B1); PG8_BAR; PG8_SCHED;
;             PG8_LDB(B0, 1, 0); PG8_LDB(B1, 1, 1); PG8_SCHED; PG8_LDA(At, 1, 0); PG8_STAGE(PG8_SA(0, 1), a2 + hstep, voffA);
.LBB0_444:
	ds_read_b128 v[130:133], v174
	ds_read_b128 v[134:137], v174 offset:1024
	ds_read_b128 v[138:141], v174 offset:2048
	ds_read_b128 v[142:145], v174 offset:3072
	ds_read_b128 v[160:163], v175
	ds_read_b128 v[164:167], v175 offset:1024
	ds_read_b128 v[168:171], v175 offset:2048
	ds_read_b128 v[178:181], v175 offset:3072
	s_add_u32 s48, s46, 0x4000
	s_addc_u32 s49, s47, 0
	s_cmp_eq_u32 s80, 12
	s_cselect_b32 s52, s31, s48
	s_cselect_b32 s53, s9, s49
	s_cselect_b32 s50, s73, s74
	s_cselect_b32 s51, s23, s75
	s_add_u32 s48, s52, 0x8000
	s_addc_u32 s49, s53, 0
	v_lshl_add_u64 v[214:215], s[46:47], 0, v[156:157]
	s_add_i32 m0, s13, 0xc000
	ds_read_b128 v[182:185], v176
	ds_read_b128 v[186:189], v176 offset:1024
	ds_read_b128 v[190:193], v176 offset:2048
	ds_read_b128 v[194:197], v176 offset:3072
	ds_read_b128 v[198:201], v176 offset:4096
	ds_read_b128 v[202:205], v176 offset:5120
	ds_read_b128 v[206:209], v176 offset:6144
	ds_read_b128 v[210:213], v176 offset:7168
	global_load_lds_dwordx4 v[214:215], off
	v_lshl_add_u64 v[214:215], s[46:47], 0, v[158:159]
	s_add_i32 m0, s13, 0xe000
	s_nop 0
	global_load_lds_dwordx4 v[214:215], off
	s_and_b64 vcc, exec, s[4:5]
	s_cbranch_vccnz .Ldw_444_0
	s_waitcnt vmcnt(8)
.Ldw_444_0:
	s_waitcnt lgkmcnt(0)
	s_barrier
	s_setprio 1
	s_waitcnt lgkmcnt(0)
	v_mfma_f32_16x16x32_bf16 v[126:129], v[130:133], v[182:185], v[126:129]
	v_mfma_f32_16x16x32_bf16 v[122:125], v[138:141], v[182:185], v[122:125]
	v_mfma_f32_16x16x32_bf16 v[118:121], v[130:133], v[190:193], v[118:121]
	v_mfma_f32_16x16x32_bf16 v[114:117], v[138:141], v[190:193], v[114:117]
	v_mfma_f32_16x16x32_bf16 v[110:113], v[130:133], v[198:201], v[110:113]
	v_mfma_f32_16x16x32_bf16 v[106:109], v[138:141], v[198:201], v[106:109]
	v_mfma_f32_16x16x32_bf16 v[102:105], v[130:133], v[206:209], v[102:105]
	v_mfma_f32_16x16x32_bf16 v[98:101], v[138:141], v[206:209], v[98:101]
	v_mfma_f32_16x16x32_bf16 v[126:129], v[134:137], v[186:189], v[126:129]
	v_mfma_f32_16x16x32_bf16 v[122:125], v[142:145], v[186:189], v[122:125]
	v_mfma_f32_16x16x32_bf16 v[118:121], v[134:137], v[194:197], v[118:121]
	v_mfma_f32_16x16x32_bf16 v[114:117], v[142:145], v[194:197], v[114:117]
	v_mfma_f32_16x16x32_bf16 v[110:113], v[134:137], v[202:205], v[110:113]
	v_mfma_f32_16x16x32_bf16 v[106:109], v[142:145], v[202:205], v[106:109]
	v_mfma_f32_16x16x32_bf16 v[102:105], v[134:137], v[210:213], v[102:105]
	v_mfma_f32_16x16x32_bf16 v[98:101], v[142:145], v[210:213], v[98:101]
	s_setprio 0
	s_setprio 1
	v_mfma_f32_16x16x32_bf16 v[66:69], v[160:163], v[182:185], v[66:69]
	v_mfma_f32_16x16x32_bf16 v[58:61], v[168:171], v[182:185], v[58:61]
	v_mfma_f32_16x16x32_bf16 v[54:57], v[160:163], v[190:193], v[54:57]
	v_mfma_f32_16x16x32_bf16 v[50:53], v[168:171], v[190:193], v[50:53]
	v_mfma_f32_16x16x32_bf16 v[46:49], v[160:163], v[198:201], v[46:49]
	v_mfma_f32_16x16x32_bf16 v[42:45], v[168:171], v[198:201], v[42:45]
	v_mfma_f32_16x16x32_bf16 v[38:41], v[160:163], v[206:209], v[38:41]
	v_mfma_f32_16x16x32_bf16 v[34:37], v[168:171], v[206:209], v[34:37]
	v_mfma_f32_16x16x32_bf16 v[66:69], v[164:167], v[186:189], v[66:69]
	v_mfma_f32_16x16x32_bf16 v[58:61], v[178:181], v[186:189], v[58:61]
	v_mfma_f32_16x16x32_bf16 v[54:57], v[164:167], v[194:197], v[54:57]
	v_mfma_f32_16x16x32_bf16 v[50:53], v[178:181], v[194:197], v[50:53]
	v_mfma_f32_16x16x32_bf16 v[46:49], v[164:167], v[202:205], v[46:49]
	v_mfma_f32_16x16x32_bf16 v[42:45], v[178:181], v[202:205], v[42:45]
	v_mfma_f32_16x16x32_bf16 v[38:41], v[164:167], v[210:213], v[38:41]
	v_mfma_f32_16x16x32_bf16 v[34:37], v[178:181], v[210:213], v[34:37]
	s_setprio 0
	s_waitcnt vmcnt(8)
	s_barrier
	s_add_i32 s81, s57, s11
	v_lshl_add_u64 v[214:215], s[50:51], 0, v[150:151]
	s_mov_b32 m0, s81
	ds_read_b128 v[182:185], v176 offset:16384
	ds_read_b128 v[186:189], v176 offset:17408
	ds_read_b128 v[190:193], v176 offset:18432
	ds_read_b128 v[194:197], v176 offset:19456
	ds_read_b128 v[198:201], v176 offset:20480
	ds_read_b128 v[202:205], v176 offset:21504
	ds_read_b128 v[206:209], v176 offset:22528
	ds_read_b128 v[210:213], v176 offset:23552
	global_load_lds_dwordx4 v[214:215], off
	s_add_i32 m0, s81, 0x2000
	s_add_u32 s82, s50, 0x4000
	v_lshl_add_u64 v[214:215], s[50:51], 0, v[146:147]
	s_addc_u32 s83, s51, 0
	s_add_i32 s81, s58, s11
	global_load_lds_dwordx4 v[214:215], off
	v_lshl_add_u64 v[214:215], s[82:83], 0, v[150:151]
	s_mov_b32 m0, s81
	s_nop 0
	global_load_lds_dwordx4 v[214:215], off
	v_lshl_add_u64 v[214:215], s[82:83], 0, v[146:147]
	s_add_i32 m0, s81, 0x2000
	s_nop 0
	global_load_lds_dwordx4 v[214:215], off
	v_lshl_add_u64 v[214:215], s[52:53], 0, v[152:153]
	s_mov_b32 m0, s13
	s_nop 0
	global_load_lds_dwordx4 v[214:215], off
	v_lshl_add_u64 v[214:215], s[52:53], 0, v[148:149]
	s_mov_b32 m0, s14
	s_nop 0
	global_load_lds_dwordx4 v[214:215], off
	s_and_b64 vcc, exec, s[4:5]
	s_cbranch_vccnz .Ldw_444_1
	s_waitcnt vmcnt(8)
; #define PG8_STAGE(bufoff, gbase, voff) do { _Pragma("unroll") for (int _i = 0; _i < 2; ++_i) \
;         __builtin_amdgcn_global_load_lds((const unsigned*)((const char*)(gbase) + (voff)[_i]), (PG8_LAS unsigned*)(lds + (bufoff) + ldsw + _i * 8192), 16, 0, 0); } while (0)
; #define PG8_LDA(dst, b, h) do { _Pragma("unroll") for (int m = 0; m < 4; ++m) _Pragma("unroll") for (int k = 0; k < 2; ++k) dst[m][k] = *(const PG8_LAS bf16x8*)(lds + PG8_SA(b, h) + aoff + m * 2048 + k * 1024); } while (0)
; #define PG8_LDB(dst, b, h) do { _Pragma("unroll") for (int n = 0; n < 2; ++n) _Pragma("unroll") for (int k = 0; k < 2; ++k) dst[n][k] = *(const PG8_LAS bf16x8*)(lds + PG8_SB(b, h) + boff + n * 2048 + k * 1024); } while (0)
; #define PG8_MMA(ai, bj, At, Bt) do { __builtin_amdgcn_s_setprio(1); _Pragma("unroll") for (int m = 0; m < 4; ++m) _Pragma("unroll") for (int n = 0; n < 2; ++n) _Pragma("unroll") for (int k = 0; k < 2; ++k) \
;         acc[ai][bj][m][n] = __builtin_amdgcn_mfma_f32_16x16x32_bf16(Bt[n][k], At[m][k], acc[ai][bj][m][n], 0, 0, 0); __builtin_amdgcn_s_setprio(0); } while (0)
; #define PG8_WAIT_V(n) asm volatile("s_waitcnt vmcnt(" #n ")" ::: "memory")
; #define PG8_WAIT_L(n) asm volatile("s_waitcnt lgkmcnt(" #n ")" ::: "memory")
; #define PG8_BAR __builtin_amdgcn_s_barrier()
; #define PG8_SCHED __builtin_amdgcn_sched_barrier(0)
; template <class Epi, class Sched, bool ALIGN_EPI = false, bool SP2 = false>
; __device__ __forceinline__ void gemm_phase(PG8_LAS unsigned char* lds, const Gemm g, const Sched& S, const Epi& E, volatile PG8_LAS unsigned* sw = nullptr) {
;     ...
;             PG8_WAIT_V(8); PG8_WAIT_L(0); PG8_BAR; PG8_MMA(1, 0, At, B0); PG8_MMA(1, 1, At, B1); PG8_BAR; PG8_SCHED;
;             PG8_LDB(B0, 1, 0); PG8_LDB(B1, 1, 1); PG8_SCHED; PG8_LDA(At, 1, 0); PG8_STAGE(PG8_SA(0, 1), a2 + hstep, voffA);
;             PG8_WAIT_V(8); PG8_WAIT_L(0); PG8_BAR; PG8_MMA(0, 0, At, B0); PG8_MMA(0, 1, At, B1); PG8_BAR; PG8_SCHED;
.Ldw_444_1:
	s_waitcnt lgkmcnt(0)
	s_barrier
	s_setprio 1
	s_waitcnt lgkmcnt(0)
	v_mfma_f32_16x16x32_bf16 v[94:97], v[130:133], v[182:185], v[94:97]
	v_mfma_f32_16x16x32_bf16 v[90:93], v[138:141], v[182:185], v[90:93]
	v_mfma_f32_16x16x32_bf16 v[86:89], v[130:133], v[190:193], v[86:89]
	v_mfma_f32_16x16x32_bf16 v[82:85], v[138:141], v[190:193], v[82:85]
	v_mfma_f32_16x16x32_bf16 v[78:81], v[130:133], v[198:201], v[78:81]
	v_mfma_f32_16x16x32_bf16 v[74:77], v[138:141], v[198:201], v[74:77]
	v_mfma_f32_16x16x32_bf16 v[70:73], v[130:133], v[206:209], v[70:73]
	v_mfma_f32_16x16x32_bf16 v[62:65], v[138:141], v[206:209], v[62:65]
	v_mfma_f32_16x16x32_bf16 v[94:97], v[134:137], v[186:189], v[94:97]
	v_mfma_f32_16x16x32_bf16 v[90:93], v[142:145], v[186:189], v[90:93]
	v_mfma_f32_16x16x32_bf16 v[86:89], v[134:137], v[194:197], v[86:89]
	v_mfma_f32_16x16x32_bf16 v[82:85], v[142:145], v[194:197], v[82:85]
	v_mfma_f32_16x16x32_bf16 v[78:81], v[134:137], v[202:205], v[78:81]
	v_mfma_f32_16x16x32_bf16 v[74:77], v[142:145], v[202:205], v[74:77]
	v_mfma_f32_16x16x32_bf16 v[70:73], v[134:137], v[210:213], v[70:73]
	v_mfma_f32_16x16x32_bf16 v[62:65], v[142:145], v[210:213], v[62:65]
	s_setprio 0
	s_setprio 1
	v_mfma_f32_16x16x32_bf16 v[30:33], v[160:163], v[182:185], v[30:33]
	v_mfma_f32_16x16x32_bf16 v[26:29], v[168:171], v[182:185], v[26:29]
	v_mfma_f32_16x16x32_bf16 v[22:25], v[160:163], v[190:193], v[22:25]
	v_mfma_f32_16x16x32_bf16 v[18:21], v[168:171], v[190:193], v[18:21]
	v_mfma_f32_16x16x32_bf16 v[14:17], v[160:163], v[198:201], v[14:17]
	v_mfma_f32_16x16x32_bf16 v[10:13], v[168:171], v[198:201], v[10:13]
	v_mfma_f32_16x16x32_bf16 v[6:9], v[160:163], v[206:209], v[6:9]
	v_mfma_f32_16x16x32_bf16 v[2:5], v[168:171], v[206:209], v[2:5]
	v_mfma_f32_16x16x32_bf16 v[30:33], v[164:167], v[186:189], v[30:33]
	v_mfma_f32_16x16x32_bf16 v[26:29], v[178:181], v[186:189], v[26:29]
	v_mfma_f32_16x16x32_bf16 v[22:25], v[164:167], v[194:197], v[22:25]
	v_mfma_f32_16x16x32_bf16 v[18:21], v[178:181], v[194:197], v[18:21]
	v_mfma_f32_16x16x32_bf16 v[14:17], v[164:167], v[202:205], v[14:17]
	v_mfma_f32_16x16x32_bf16 v[10:13], v[178:181], v[202:205], v[10:13]
	v_mfma_f32_16x16x32_bf16 v[6:9], v[164:167], v[210:213], v[6:9]
	v_mfma_f32_16x16x32_bf16 v[2:5], v[178:181], v[210:213], v[2:5]
	s_setprio 0
	s_waitcnt vmcnt(8)
	s_barrier
	s_add_i32 s81, 0, 0x18000
	s_add_i32 s82, 0, 0x1c000
	v_add_u32_e32 v142, s81, v173
	v_add_u32_e32 v154, s82, v173
	ds_read_b128 v[130:133], v142
	ds_read_b128 v[134:137], v142 offset:1024
	ds_read_b128 v[138:141], v142 offset:2048
	ds_read_b128 v[142:145], v142 offset:3072
	ds_read_b128 v[160:163], v154
	ds_read_b128 v[164:167], v154 offset:1024
	ds_read_b128 v[168:171], v154 offset:2048
	ds_read_b128 v[178:181], v154 offset:3072
	s_add_u32 s52, s52, 0x4000
	s_addc_u32 s53, s53, 0
	s_mov_b32 m0, s15
	v_lshl_add_u64 v[214:215], s[52:53], 0, v[152:153]
	ds_read_b128 v[182:185], v176 offset:32768
	ds_read_b128 v[186:189], v176 offset:33792
	ds_read_b128 v[190:193], v176 offset:34816
	ds_read_b128 v[194:197], v176 offset:35840
	ds_read_b128 v[198:201], v176 offset:36864
	ds_read_b128 v[202:205], v176 offset:37888
	ds_read_b128 v[206:209], v176 offset:38912
	ds_read_b128 v[210:213], v176 offset:39936
	global_load_lds_dwordx4 v[214:215], off
	v_lshl_add_u64 v[214:215], s[52:53], 0, v[148:149]
	s_mov_b32 m0, s33
	s_nop 0
	global_load_lds_dwordx4 v[214:215], off
	s_and_b64 vcc, exec, s[4:5]
	s_cbranch_vccnz .Ldw_444_2
	s_waitcnt vmcnt(8)
; #define PG8_STAGE(bufoff, gbase, voff) do { _Pragma("unroll") for (int _i = 0; _i < 2; ++_i) \
;         __builtin_amdgcn_global_load_lds((const unsigned*)((const char*)(gbase) + (voff)[_i]), (PG8_LAS unsigned*)(lds + (bufoff) + ldsw + _i * 8192), 16, 0, 0); } while (0)
; template <class Epi, class Sched, bool ALIGN_EPI = false, bool SP2 = false>
; __device__ __forceinline__ void gemm_phase(PG8_LAS unsigned char* lds, const Gemm g, const Sched& S, const Epi& E, volatile PG8_LAS unsigned* sw = nullptr) {
;     ...
;             PG8_LDB(B0, 1, 0); PG8_LDB(B1, 1, 1); PG8_SCHED; PG8_LDA(At, 1, 0); PG8_STAGE(PG8_SA(0, 1), a2 + hstep, voffA);
;             PG8_WAIT_V(8); PG8_WAIT_L(0); PG8_BAR; PG8_MMA(0, 0, At, B0); PG8_MMA(0, 1, At, B1); PG8_BAR; PG8_SCHED;
;             PG8_LDA(At, 1, 1); PG8_STAGE(PG8_SB(1, 0), b3, voffB); PG8_STAGE(PG8_SB(1, 1), b3 + hstep, voffB); PG8_STAGE(PG8_SA(1, 0), a3, voffA);
;             PG8_WAIT_V(8); PG8_WAIT_L(0); PG8_BAR; PG8_MMA(1, 0, At, B0); PG8_MMA(1, 1, At, B1); PG8_BAR; PG8_SCHED;
;             } else {
;             PG8_LDB(B0, 0, 0); PG8_SCHED; PG8_LDA(At, 0, 0); PG8_STAGE(PG8_SA(1, 1), a1 + hstep, voffA);
;             PG8_WAIT_L(8); PG8_BAR; PG8_WAIT_L(0); PG8_MMA(0, 0, At, B0); PG8_BAR; PG8_SCHED;
;             PG8_LDB(B1, 0, 1); PG8_STAGE(PG8_SB(0, 0), b2, voffB);
;             PG8_BAR; PG8_WAIT_L(0); PG8_MMA(0, 1, At, B1); PG8_BAR;
;             PG8_LDA(At, 0, 1); PG8_STAGE(PG8_SA(0, 0), a2, voffA);
;             PG8_BAR; PG8_WAIT_L(0); PG8_MMA(1, 0, At, B0); PG8_BAR; PG8_SCHED;
;             PG8_STAGE(PG8_SB(0, 1), b2 + hstep, voffB);
;             PG8_WAIT_V(6); PG8_BAR; PG8_MMA(1, 1, At, B1); PG8_BAR;
;             PG8_LDB(B0, 1, 0); PG8_SCHED; PG8_LDA(At, 1, 0); PG8_STAGE(PG8_SA(0, 1), a2 + hstep, voffA);
;             PG8_WAIT_L(8); PG8_BAR; PG8_WAIT_L(0); PG8_MMA(0, 0, At, B0); PG8_BAR; PG8_SCHED;
;             PG8_LDB(B1, 1, 1); PG8_STAGE(PG8_SB(1, 0), b3, voffB);
;             PG8_BAR; PG8_WAIT_L(0); PG8_MMA(0, 1, At, B1); PG8_BAR;
;             PG8_LDA(At, 1, 1); PG8_STAGE(PG8_SA(1, 0), a3, voffA);
;             PG8_BAR; PG8_WAIT_L(0); PG8_MMA(1, 0, At, B0); PG8_BAR; PG8_SCHED;
;             PG8_STAGE(PG8_SB(1, 1), b3 + hstep, voffB);
;             PG8_WAIT_V(6); PG8_BAR; PG8_MMA(1, 1, At, B1); PG8_BAR;
;             }
;         }
;         if constexpr (ALIGN_EPI) { if (wr == 0) PG8_BAR; }
.Ldw_444_2:
	s_waitcnt lgkmcnt(0)
	s_barrier
	s_setprio 1
	s_waitcnt lgkmcnt(0)
	v_mfma_f32_16x16x32_bf16 v[126:129], v[130:133], v[182:185], v[126:129]
	v_mfma_f32_16x16x32_bf16 v[122:125], v[138:141], v[182:185], v[122:125]
	v_mfma_f32_16x16x32_bf16 v[118:121], v[130:133], v[190:193], v[118:121]
	v_mfma_f32_16x16x32_bf16 v[114:117], v[138:141], v[190:193], v[114:117]
	v_mfma_f32_16x16x32_bf16 v[110:113], v[130:133], v[198:201], v[110:113]
	v_mfma_f32_16x16x32_bf16 v[106:109], v[138:141], v[198:201], v[106:109]
	v_mfma_f32_16x16x32_bf16 v[102:105], v[130:133], v[206:209], v[102:105]
	v_mfma_f32_16x16x32_bf16 v[98:101], v[138:141], v[206:209], v[98:101]
	v_mfma_f32_16x16x32_bf16 v[126:129], v[134:137], v[186:189], v[126:129]
	v_mfma_f32_16x16x32_bf16 v[122:125], v[142:145], v[186:189], v[122:125]
	v_mfma_f32_16x16x32_bf16 v[118:121], v[134:137], v[194:197], v[118:121]
	v_mfma_f32_16x16x32_bf16 v[114:117], v[142:145], v[194:197], v[114:117]
	v_mfma_f32_16x16x32_bf16 v[110:113], v[134:137], v[202:205], v[110:113]
	v_mfma_f32_16x16x32_bf16 v[106:109], v[142:145], v[202:205], v[106:109]
	v_mfma_f32_16x16x32_bf16 v[102:105], v[134:137], v[210:213], v[102:105]
	v_mfma_f32_16x16x32_bf16 v[98:101], v[142:145], v[210:213], v[98:101]
	s_setprio 0
	s_setprio 1
	v_mfma_f32_16x16x32_bf16 v[66:69], v[160:163], v[182:185], v[66:69]
	v_mfma_f32_16x16x32_bf16 v[58:61], v[168:171], v[182:185], v[58:61]
	v_mfma_f32_16x16x32_bf16 v[54:57], v[160:163], v[190:193], v[54:57]
	v_mfma_f32_16x16x32_bf16 v[50:53], v[168:171], v[190:193], v[50:53]
	v_mfma_f32_16x16x32_bf16 v[46:49], v[160:163], v[198:201], v[46:49]
	v_mfma_f32_16x16x32_bf16 v[42:45], v[168:171], v[198:201], v[42:45]
	v_mfma_f32_16x16x32_bf16 v[38:41], v[160:163], v[206:209], v[38:41]
	v_mfma_f32_16x16x32_bf16 v[34:37], v[168:171], v[206:209], v[34:37]
	v_mfma_f32_16x16x32_bf16 v[66:69], v[164:167], v[186:189], v[66:69]
	v_mfma_f32_16x16x32_bf16 v[58:61], v[178:181], v[186:189], v[58:61]
	v_mfma_f32_16x16x32_bf16 v[54:57], v[164:167], v[194:197], v[54:57]
	v_mfma_f32_16x16x32_bf16 v[50:53], v[178:181], v[194:197], v[50:53]
	v_mfma_f32_16x16x32_bf16 v[46:49], v[164:167], v[202:205], v[46:49]
	v_mfma_f32_16x16x32_bf16 v[42:45], v[178:181], v[202:205], v[42:45]
	v_mfma_f32_16x16x32_bf16 v[38:41], v[164:167], v[210:213], v[38:41]
	v_mfma_f32_16x16x32_bf16 v[34:37], v[178:181], v[210:213], v[34:37]
	s_setprio 0
	s_waitcnt vmcnt(8)
	s_barrier
	s_add_u32 s52, s50, 0x8000
	s_addc_u32 s53, s51, 0
	s_add_i32 s81, s81, s11
	v_lshl_add_u64 v[214:215], s[52:53], 0, v[150:151]
	s_mov_b32 m0, s81
	ds_read_b128 v[182:185], v176 offset:49152
	ds_read_b128 v[186:189], v176 offset:50176
	ds_read_b128 v[190:193], v176 offset:51200
	ds_read_b128 v[194:197], v176 offset:52224
	ds_read_b128 v[198:201], v176 offset:53248
	ds_read_b128 v[202:205], v176 offset:54272
	ds_read_b128 v[206:209], v176 offset:55296
	ds_read_b128 v[210:213], v176 offset:56320
	global_load_lds_dwordx4 v[214:215], off
	s_add_i32 m0, s81, 0x2000
	s_add_u32 s50, s50, 0xc000
	v_lshl_add_u64 v[214:215], s[52:53], 0, v[146:147]
	s_addc_u32 s51, s51, 0
	s_add_i32 s52, s82, s11
	global_load_lds_dwordx4 v[214:215], off
	v_lshl_add_u64 v[214:215], s[50:51], 0, v[150:151]
	s_mov_b32 m0, s52
	s_nop 0
	global_load_lds_dwordx4 v[214:215], off
	v_lshl_add_u64 v[214:215], s[50:51], 0, v[146:147]
	s_add_i32 m0, s52, 0x2000
	s_nop 0
	global_load_lds_dwordx4 v[214:215], off
	v_lshl_add_u64 v[214:215], s[48:49], 0, v[152:153]
	s_mov_b32 m0, s41
	s_nop 0
	global_load_lds_dwordx4 v[214:215], off
	v_lshl_add_u64 v[214:215], s[48:49], 0, v[148:149]
	s_mov_b32 m0, s42
	s_nop 0
	global_load_lds_dwordx4 v[214:215], off
	s_and_b64 vcc, exec, s[4:5]
	s_cbranch_vccnz .Ldw_444_3
	s_waitcnt vmcnt(8)
.Ldw_444_3:
	s_waitcnt lgkmcnt(0)
	s_barrier
	s_setprio 1
	s_waitcnt lgkmcnt(0)
	v_mfma_f32_16x16x32_bf16 v[94:97], v[130:133], v[182:185], v[94:97]
	v_mfma_f32_16x16x32_bf16 v[90:93], v[138:141], v[182:185], v[90:93]
	v_mfma_f32_16x16x32_bf16 v[86:89], v[130:133], v[190:193], v[86:89]
	v_mfma_f32_16x16x32_bf16 v[82:85], v[138:141], v[190:193], v[82:85]
	v_mfma_f32_16x16x32_bf16 v[78:81], v[130:133], v[198:201], v[78:81]
	v_mfma_f32_16x16x32_bf16 v[74:77], v[138:141], v[198:201], v[74:77]
	v_mfma_f32_16x16x32_bf16 v[70:73], v[130:133], v[206:209], v[70:73]
	v_mfma_f32_16x16x32_bf16 v[62:65], v[138:141], v[206:209], v[62:65]
	v_mfma_f32_16x16x32_bf16 v[94:97], v[134:137], v[186:189], v[94:97]
	v_mfma_f32_16x16x32_bf16 v[90:93], v[142:145], v[186:189], v[90:93]
	v_mfma_f32_16x16x32_bf16 v[86:89], v[134:137], v[194:197], v[86:89]
	v_mfma_f32_16x16x32_bf16 v[82:85], v[142:145], v[194:197], v[82:85]
	v_mfma_f32_16x16x32_bf16 v[78:81], v[134:137], v[202:205], v[78:81]
	v_mfma_f32_16x16x32_bf16 v[74:77], v[142:145], v[202:205], v[74:77]
	v_mfma_f32_16x16x32_bf16 v[70:73], v[134:137], v[210:213], v[70:73]
	v_mfma_f32_16x16x32_bf16 v[62:65], v[142:145], v[210:213], v[62:65]
	s_setprio 0
	s_setprio 1
	v_mfma_f32_16x16x32_bf16 v[30:33], v[160:163], v[182:185], v[30:33]
	v_mfma_f32_16x16x32_bf16 v[26:29], v[168:171], v[182:185], v[26:29]
	v_mfma_f32_16x16x32_bf16 v[22:25], v[160:163], v[190:193], v[22:25]
	v_mfma_f32_16x16x32_bf16 v[18:21], v[168:171], v[190:193], v[18:21]
	v_mfma_f32_16x16x32_bf16 v[14:17], v[160:163], v[198:201], v[14:17]
	v_mfma_f32_16x16x32_bf16 v[10:13], v[168:171], v[198:201], v[10:13]
	v_mfma_f32_16x16x32_bf16 v[6:9], v[160:163], v[206:209], v[6:9]
	v_mfma_f32_16x16x32_bf16 v[2:5], v[168:171], v[206:209], v[2:5]
	v_mfma_f32_16x16x32_bf16 v[30:33], v[164:167], v[186:189], v[30:33]
	v_mfma_f32_16x16x32_bf16 v[26:29], v[178:181], v[186:189], v[26:29]
	v_mfma_f32_16x16x32_bf16 v[22:25], v[164:167], v[194:197], v[22:25]
	v_mfma_f32_16x16x32_bf16 v[18:21], v[178:181], v[194:197], v[18:21]
	v_mfma_f32_16x16x32_bf16 v[14:17], v[164:167], v[202:205], v[14:17]
	v_mfma_f32_16x16x32_bf16 v[10:13], v[178:181], v[202:205], v[10:13]
	v_mfma_f32_16x16x32_bf16 v[6:9], v[164:167], v[210:213], v[6:9]
	v_mfma_f32_16x16x32_bf16 v[2:5], v[178:181], v[210:213], v[2:5]
	s_setprio 0
	s_waitcnt vmcnt(8)
	s_barrier
	s_add_i32 s80, s80, 2
	s_add_u32 s46, s46, 0x10000
	s_addc_u32 s47, s47, 0
	s_add_u32 s74, s74, 0x10000
	s_addc_u32 s75, s75, 0
	s_cmp_gt_u32 s80, 13
	s_cbranch_scc0 .LBB0_444
	s_and_b64 vcc, exec, s[4:5]
	s_cbranch_vccz .LBB0_447
	s_barrier

; #define PG8_STAGE(bufoff, gbase, voff) do { _Pragma("unroll") for (int _i = 0; _i < 2; ++_i) \
;         __builtin_amdgcn_global_load_lds((const unsigned*)((const char*)(gbase) + (voff)[_i]), (PG8_LAS unsigned*)(lds + (bufoff) + ldsw + _i * 8192), 16, 0, 0); } while (0)
; #define PG8_LDA(dst, b, h) do { _Pragma("unroll") for (int m = 0; m < 4; ++m) _Pragma("unroll") for (int k = 0; k < 2; ++k) dst[m][k] = *(const PG8_LAS bf16x8*)(lds + PG8_SA(b, h) + aoff + m * 2048 + k * 1024); } while (0)
; #define PG8_LDB(dst, b, h) do { _Pragma("unroll") for (int n = 0; n < 2; ++n) _Pragma("unroll") for (int k = 0; k < 2; ++k) dst[n][k] = *(const PG8_LAS bf16x8*)(lds + PG8_SB(b, h) + boff + n * 2048 + k * 1024); } while (0)
; #define PG8_MMA(ai, bj, At, Bt) do { __builtin_amdgcn_s_setprio(1); _Pragma("unroll") for (int m = 0; m < 4; ++m) _Pragma("unroll") for (int n = 0; n < 2; ++n) _Pragma("unroll") for (int k = 0; k < 2; ++k) \
;         acc[ai][bj][m][n] = __builtin_amdgcn_mfma_f32_16x16x32_bf16(Bt[n][k], At[m][k], acc[ai][bj][m][n], 0, 0, 0); __builtin_amdgcn_s_setprio(0); } while (0)
; #define PG8_WAIT_V(n) asm volatile("s_waitcnt vmcnt(" #n ")" ::: "memory")
; #define PG8_WAIT_L(n) asm volatile("s_waitcnt lgkmcnt(" #n ")" ::: "memory")
; #define PG8_BAR __builtin_amdgcn_s_barrier()
; #define PG8_SCHED __builtin_amdgcn_sched_barrier(0)
; template <class Epi, class Sched, bool ALIGN_EPI = false, bool SP2 = false>
; __device__ __forceinline__ void gemm_phase(PG8_LAS unsigned char* lds, const Gemm g, const Sched& S, const Epi& E, volatile PG8_LAS unsigned* sw = nullptr) {
;     ...
;             PG8_LDB(B0, 0, 0); PG8_LDB(B1, 0, 1); PG8_SCHED; PG8_LDA(At, 0, 0); PG8_STAGE(PG8_SA(1, 1), a1 + hstep, voffA);
;             PG8_WAIT_V(8); PG8_WAIT_L(0); PG8_BAR; PG8_MMA(0, 0, At, B0); PG8_MMA(0, 1, At, B1); PG8_BAR; PG8_SCHED;
;             PG8_LDA(At, 0, 1); PG8_STAGE(PG8_SB(0, 0), b2, voffB); PG8_STAGE(PG8_SB(0, 1), b2 + hstep, voffB); PG8_STAGE(PG8_SA(0, 0), a2, voffA);
;             PG8_WAIT_V(8); PG8_WAIT_L(0); PG8_BAR; PG8_MMA(1, 0, At, B0); PG8_MMA(1, 1, At, B1); PG8_BAR; PG8_SCHED;
;             PG8_LDB(B0, 1, 0); PG8_LDB(B1, 1, 1); PG8_SCHED; PG8_LDA(At, 1, 0); PG8_STAGE(PG8_SA(0, 1), a2 + hstep, voffA);
.LBB0_532:
	ds_read_b128 v[130:133], v230
	ds_read_b128 v[134:137], v230 offset:1024
	ds_read_b128 v[138:141], v230 offset:2048
	ds_read_b128 v[142:145], v230 offset:3072
	ds_read_b128 v[146:149], v231
	ds_read_b128 v[150:153], v231 offset:1024
	ds_read_b128 v[168:171], v231 offset:2048
	ds_read_b128 v[172:175], v231 offset:3072
	s_add_u32 s2, s0, 0x10000
	s_addc_u32 s3, s1, 0
	s_cmp_eq_u32 s85, 12
	s_cselect_b32 s8, s57, s2
	s_cselect_b32 s9, s37, s3
	s_cselect_b32 s6, s66, s67
	s_cselect_b32 s7, s39, s84
	s_add_u32 s4, s8, 0x8000
	s_addc_u32 s5, s9, 0
	v_lshl_add_u64 v[208:209], s[0:1], 0, v[164:165]
	s_add_i32 m0, s15, 0xc000
	ds_read_b128 v[176:179], v232
	ds_read_b128 v[180:183], v232 offset:1024
	ds_read_b128 v[184:187], v232 offset:2048
	ds_read_b128 v[188:191], v232 offset:3072
	ds_read_b128 v[192:195], v232 offset:4096
	ds_read_b128 v[196:199], v232 offset:5120
	ds_read_b128 v[200:203], v232 offset:6144
	ds_read_b128 v[204:207], v232 offset:7168
	global_load_lds_dwordx4 v[208:209], off
	v_lshl_add_u64 v[208:209], s[0:1], 0, v[166:167]
	s_add_i32 m0, s15, 0xe000
	s_nop 0
	global_load_lds_dwordx4 v[208:209], off
	s_and_b64 vcc, exec, s[28:29]
	s_cbranch_vccnz .Ldw_532_0
	s_waitcnt vmcnt(8)
.Ldw_532_0:
	s_waitcnt lgkmcnt(0)
	s_barrier
	s_waitcnt lgkmcnt(0)
	v_mfma_f32_16x16x32_bf16 v[118:121], v[130:133], v[176:179], v[118:121]
	v_mfma_f32_16x16x32_bf16 v[122:125], v[138:141], v[176:179], v[122:125]
	v_mfma_f32_16x16x32_bf16 v[78:81], v[130:133], v[184:187], v[78:81]
	v_mfma_f32_16x16x32_bf16 v[74:77], v[138:141], v[184:187], v[74:77]
	v_mfma_f32_16x16x32_bf16 v[58:61], v[130:133], v[192:195], v[58:61]
	v_mfma_f32_16x16x32_bf16 v[54:57], v[138:141], v[192:195], v[54:57]
	v_mfma_f32_16x16x32_bf16 v[126:129], v[130:133], v[200:203], v[126:129]
	v_mfma_f32_16x16x32_bf16 v[114:117], v[138:141], v[200:203], v[114:117]
	v_mfma_f32_16x16x32_bf16 v[118:121], v[134:137], v[180:183], v[118:121]
	v_mfma_f32_16x16x32_bf16 v[122:125], v[142:145], v[180:183], v[122:125]
	v_mfma_f32_16x16x32_bf16 v[78:81], v[134:137], v[188:191], v[78:81]
	v_mfma_f32_16x16x32_bf16 v[74:77], v[142:145], v[188:191], v[74:77]
	v_mfma_f32_16x16x32_bf16 v[58:61], v[134:137], v[196:199], v[58:61]
	v_mfma_f32_16x16x32_bf16 v[54:57], v[142:145], v[196:199], v[54:57]
	v_mfma_f32_16x16x32_bf16 v[126:129], v[134:137], v[204:207], v[126:129]
	v_mfma_f32_16x16x32_bf16 v[114:117], v[142:145], v[204:207], v[114:117]
	v_mfma_f32_16x16x32_bf16 v[110:113], v[146:149], v[176:179], v[110:113]
	v_mfma_f32_16x16x32_bf16 v[98:101], v[168:171], v[176:179], v[98:101]
	v_mfma_f32_16x16x32_bf16 v[70:73], v[146:149], v[184:187], v[70:73]
	v_mfma_f32_16x16x32_bf16 v[66:69], v[168:171], v[184:187], v[66:69]
	v_mfma_f32_16x16x32_bf16 v[42:45], v[146:149], v[192:195], v[42:45]
	v_mfma_f32_16x16x32_bf16 v[34:37], v[168:171], v[192:195], v[34:37]
	v_mfma_f32_16x16x32_bf16 v[102:105], v[146:149], v[200:203], v[102:105]
	v_mfma_f32_16x16x32_bf16 v[90:93], v[168:171], v[200:203], v[90:93]
	v_mfma_f32_16x16x32_bf16 v[110:113], v[150:153], v[180:183], v[110:113]
	v_mfma_f32_16x16x32_bf16 v[98:101], v[172:175], v[180:183], v[98:101]
	v_mfma_f32_16x16x32_bf16 v[70:73], v[150:153], v[188:191], v[70:73]
	v_mfma_f32_16x16x32_bf16 v[66:69], v[172:175], v[188:191], v[66:69]
	v_mfma_f32_16x16x32_bf16 v[42:45], v[150:153], v[196:199], v[42:45]
	v_mfma_f32_16x16x32_bf16 v[34:37], v[172:175], v[196:199], v[34:37]
	v_mfma_f32_16x16x32_bf16 v[102:105], v[150:153], v[204:207], v[102:105]
	v_mfma_f32_16x16x32_bf16 v[90:93], v[172:175], v[204:207], v[90:93]
	s_waitcnt vmcnt(8)
	s_barrier
	s_add_i32 s0, s75, s13
	v_lshl_add_u64 v[208:209], s[6:7], 0, v[156:157]
	s_mov_b32 m0, s0
	ds_read_b128 v[176:179], v232 offset:16384
	ds_read_b128 v[180:183], v232 offset:17408
	ds_read_b128 v[184:187], v232 offset:18432
	ds_read_b128 v[188:191], v232 offset:19456
	ds_read_b128 v[192:195], v232 offset:20480
	ds_read_b128 v[196:199], v232 offset:21504
	ds_read_b128 v[200:203], v232 offset:22528
	ds_read_b128 v[204:207], v232 offset:23552
	global_load_lds_dwordx4 v[208:209], off
	s_add_i32 m0, s0, 0x2000
	s_add_u32 s0, s6, 0x4000
	v_lshl_add_u64 v[208:209], s[6:7], 0, v[160:161]
	s_addc_u32 s1, s7, 0
	s_add_i32 s86, s80, s13
	global_load_lds_dwordx4 v[208:209], off
	v_lshl_add_u64 v[208:209], s[0:1], 0, v[156:157]
	s_mov_b32 m0, s86
	s_nop 0
	global_load_lds_dwordx4 v[208:209], off
	v_lshl_add_u64 v[208:209], s[0:1], 0, v[160:161]
	s_add_i32 m0, s86, 0x2000
	s_nop 0
	global_load_lds_dwordx4 v[208:209], off
	v_lshl_add_u64 v[208:209], s[8:9], 0, v[154:155]
	s_mov_b32 m0, s15
	s_nop 0
	global_load_lds_dwordx4 v[208:209], off
	v_lshl_add_u64 v[208:209], s[8:9], 0, v[158:159]
	s_mov_b32 m0, s33
	s_nop 0
	global_load_lds_dwordx4 v[208:209], off
	s_and_b64 vcc, exec, s[28:29]
	s_cbranch_vccnz .Ldw_532_1
	s_waitcnt vmcnt(8)
; #define PG8_STAGE(bufoff, gbase, voff) do { _Pragma("unroll") for (int _i = 0; _i < 2; ++_i) \
;         __builtin_amdgcn_global_load_lds((const unsigned*)((const char*)(gbase) + (voff)[_i]), (PG8_LAS unsigned*)(lds + (bufoff) + ldsw + _i * 8192), 16, 0, 0); } while (0)
; #define PG8_LDA(dst, b, h) do { _Pragma("unroll") for (int m = 0; m < 4; ++m) _Pragma("unroll") for (int k = 0; k < 2; ++k) dst[m][k] = *(const PG8_LAS bf16x8*)(lds + PG8_SA(b, h) + aoff + m * 2048 + k * 1024); } while (0)
; #define PG8_LDB(dst, b, h) do { _Pragma("unroll") for (int n = 0; n < 2; ++n) _Pragma("unroll") for (int k = 0; k < 2; ++k) dst[n][k] = *(const PG8_LAS bf16x8*)(lds + PG8_SB(b, h) + boff + n * 2048 + k * 1024); } while (0)
; #define PG8_MMA(ai, bj, At, Bt) do { __builtin_amdgcn_s_setprio(1); _Pragma("unroll") for (int m = 0; m < 4; ++m) _Pragma("unroll") for (int n = 0; n < 2; ++n) _Pragma("unroll") for (int k = 0; k < 2; ++k) \
;         acc[ai][bj][m][n] = __builtin_amdgcn_mfma_f32_16x16x32_bf16(Bt[n][k], At[m][k], acc[ai][bj][m][n], 0, 0, 0); __builtin_amdgcn_s_setprio(0); } while (0)
; #define PG8_WAIT_V(n) asm volatile("s_waitcnt vmcnt(" #n ")" ::: "memory")
; #define PG8_WAIT_L(n) asm volatile("s_waitcnt lgkmcnt(" #n ")" ::: "memory")
; #define PG8_BAR __builtin_amdgcn_s_barrier()
; #define PG8_SCHED __builtin_amdgcn_sched_barrier(0)
; template <class Epi, class Sched, bool ALIGN_EPI = false, bool SP2 = false>
; __device__ __forceinline__ void gemm_phase(PG8_LAS unsigned char* lds, const Gemm g, const Sched& S, const Epi& E, volatile PG8_LAS unsigned* sw = nullptr) {
;     ...
;             PG8_WAIT_V(8); PG8_WAIT_L(0); PG8_BAR; PG8_MMA(1, 0, At, B0); PG8_MMA(1, 1, At, B1); PG8_BAR; PG8_SCHED;
;             PG8_LDB(B0, 1, 0); PG8_LDB(B1, 1, 1); PG8_SCHED; PG8_LDA(At, 1, 0); PG8_STAGE(PG8_SA(0, 1), a2 + hstep, voffA);
;             PG8_WAIT_V(8); PG8_WAIT_L(0); PG8_BAR; PG8_MMA(0, 0, At, B0); PG8_MMA(0, 1, At, B1); PG8_BAR; PG8_SCHED;
.Ldw_532_1:
	s_waitcnt lgkmcnt(0)
	s_barrier
	s_waitcnt lgkmcnt(0)
	v_mfma_f32_16x16x32_bf16 v[94:97], v[130:133], v[176:179], v[94:97]
	v_mfma_f32_16x16x32_bf16 v[106:109], v[138:141], v[176:179], v[106:109]
	v_mfma_f32_16x16x32_bf16 v[38:41], v[130:133], v[184:187], v[38:41]
	v_mfma_f32_16x16x32_bf16 v[26:29], v[138:141], v[184:187], v[26:29]
	v_mfma_f32_16x16x32_bf16 v[46:49], v[130:133], v[192:195], v[46:49]
	v_mfma_f32_16x16x32_bf16 v[62:65], v[138:141], v[192:195], v[62:65]
	v_mfma_f32_16x16x32_bf16 v[2:5], v[130:133], v[200:203], v[2:5]
	v_mfma_f32_16x16x32_bf16 v[18:21], v[138:141], v[200:203], v[18:21]
	v_mfma_f32_16x16x32_bf16 v[94:97], v[134:137], v[180:183], v[94:97]
	v_mfma_f32_16x16x32_bf16 v[106:109], v[142:145], v[180:183], v[106:109]
	v_mfma_f32_16x16x32_bf16 v[38:41], v[134:137], v[188:191], v[38:41]
	v_mfma_f32_16x16x32_bf16 v[26:29], v[142:145], v[188:191], v[26:29]
	v_mfma_f32_16x16x32_bf16 v[46:49], v[134:137], v[196:199], v[46:49]
	v_mfma_f32_16x16x32_bf16 v[62:65], v[142:145], v[196:199], v[62:65]
	v_mfma_f32_16x16x32_bf16 v[2:5], v[134:137], v[204:207], v[2:5]
	v_mfma_f32_16x16x32_bf16 v[18:21], v[142:145], v[204:207], v[18:21]
	v_mfma_f32_16x16x32_bf16 v[86:89], v[146:149], v[176:179], v[86:89]
	v_mfma_f32_16x16x32_bf16 v[82:85], v[168:171], v[176:179], v[82:85]
	v_mfma_f32_16x16x32_bf16 v[14:17], v[146:149], v[184:187], v[14:17]
	v_mfma_f32_16x16x32_bf16 v[10:13], v[168:171], v[184:187], v[10:13]
	v_mfma_f32_16x16x32_bf16 v[30:33], v[146:149], v[192:195], v[30:33]
	v_mfma_f32_16x16x32_bf16 v[50:53], v[168:171], v[192:195], v[50:53]
	v_mfma_f32_16x16x32_bf16 v[6:9], v[146:149], v[200:203], v[6:9]
	v_mfma_f32_16x16x32_bf16 v[22:25], v[168:171], v[200:203], v[22:25]
	v_mfma_f32_16x16x32_bf16 v[86:89], v[150:153], v[180:183], v[86:89]
	v_mfma_f32_16x16x32_bf16 v[82:85], v[172:175], v[180:183], v[82:85]
	v_mfma_f32_16x16x32_bf16 v[14:17], v[150:153], v[188:191], v[14:17]
	v_mfma_f32_16x16x32_bf16 v[10:13], v[172:175], v[188:191], v[10:13]
	v_mfma_f32_16x16x32_bf16 v[30:33], v[150:153], v[196:199], v[30:33]
	v_mfma_f32_16x16x32_bf16 v[50:53], v[172:175], v[196:199], v[50:53]
	v_mfma_f32_16x16x32_bf16 v[6:9], v[150:153], v[204:207], v[6:9]
	v_mfma_f32_16x16x32_bf16 v[22:25], v[172:175], v[204:207], v[22:25]
	s_waitcnt vmcnt(8)
	s_barrier
	s_add_i32 s86, 0, 0x18000
	s_add_i32 s87, 0, 0x1c000
	v_add_u32_e32 v142, s86, v229
	v_add_u32_e32 v162, s87, v229
	ds_read_b128 v[130:133], v142
	ds_read_b128 v[134:137], v142 offset:1024
	ds_read_b128 v[138:141], v142 offset:2048
	ds_read_b128 v[142:145], v142 offset:3072
	ds_read_b128 v[146:149], v162
	ds_read_b128 v[150:153], v162 offset:1024
	ds_read_b128 v[168:171], v162 offset:2048
	ds_read_b128 v[172:175], v162 offset:3072
	s_add_u32 s0, s8, 0x4000
	s_addc_u32 s1, s9, 0
	s_mov_b32 m0, s40
	v_lshl_add_u64 v[208:209], s[0:1], 0, v[154:155]
	ds_read_b128 v[176:179], v232 offset:32768
	ds_read_b128 v[180:183], v232 offset:33792
	ds_read_b128 v[184:187], v232 offset:34816
	ds_read_b128 v[188:191], v232 offset:35840
	ds_read_b128 v[192:195], v232 offset:36864
	ds_read_b128 v[196:199], v232 offset:37888
	ds_read_b128 v[200:203], v232 offset:38912
	ds_read_b128 v[204:207], v232 offset:39936
	global_load_lds_dwordx4 v[208:209], off
	v_lshl_add_u64 v[208:209], s[0:1], 0, v[158:159]
	s_mov_b32 m0, s41
	s_nop 0
	global_load_lds_dwordx4 v[208:209], off
	s_and_b64 vcc, exec, s[28:29]
	s_cbranch_vccnz .Ldw_532_2
	s_waitcnt vmcnt(8)
; #define PG8_STAGE(bufoff, gbase, voff) do { _Pragma("unroll") for (int _i = 0; _i < 2; ++_i) \
;         __builtin_amdgcn_global_load_lds((const unsigned*)((const char*)(gbase) + (voff)[_i]), (PG8_LAS unsigned*)(lds + (bufoff) + ldsw + _i * 8192), 16, 0, 0); } while (0)
; #define PG8_LDA(dst, b, h) do { _Pragma("unroll") for (int m = 0; m < 4; ++m) _Pragma("unroll") for (int k = 0; k < 2; ++k) dst[m][k] = *(const PG8_LAS bf16x8*)(lds + PG8_SA(b, h) + aoff + m * 2048 + k * 1024); } while (0)
; #define PG8_LDB(dst, b, h) do { _Pragma("unroll") for (int n = 0; n < 2; ++n) _Pragma("unroll") for (int k = 0; k < 2; ++k) dst[n][k] = *(const PG8_LAS bf16x8*)(lds + PG8_SB(b, h) + boff + n * 2048 + k * 1024); } while (0)
; #define PG8_MMA(ai, bj, At, Bt) do { __builtin_amdgcn_s_setprio(1); _Pragma("unroll") for (int m = 0; m < 4; ++m) _Pragma("unroll") for (int n = 0; n < 2; ++n) _Pragma("unroll") for (int k = 0; k < 2; ++k) \
;         acc[ai][bj][m][n] = __builtin_amdgcn_mfma_f32_16x16x32_bf16(Bt[n][k], At[m][k], acc[ai][bj][m][n], 0, 0, 0); __builtin_amdgcn_s_setprio(0); } while (0)
; #define PG8_WAIT_V(n) asm volatile("s_waitcnt vmcnt(" #n ")" ::: "memory")
; #define PG8_WAIT_L(n) asm volatile("s_waitcnt lgkmcnt(" #n ")" ::: "memory")
; #define PG8_BAR __builtin_amdgcn_s_barrier()
; #define PG8_SCHED __builtin_amdgcn_sched_barrier(0)
; template <class Epi, class Sched, bool ALIGN_EPI = false, bool SP2 = false>
; __device__ __forceinline__ void gemm_phase(PG8_LAS unsigned char* lds, const Gemm g, const Sched& S, const Epi& E, volatile PG8_LAS unsigned* sw = nullptr) {
;     ...
;             PG8_LDB(B0, 1, 0); PG8_LDB(B1, 1, 1); PG8_SCHED; PG8_LDA(At, 1, 0); PG8_STAGE(PG8_SA(0, 1), a2 + hstep, voffA);
;             PG8_WAIT_V(8); PG8_WAIT_L(0); PG8_BAR; PG8_MMA(0, 0, At, B0); PG8_MMA(0, 1, At, B1); PG8_BAR; PG8_SCHED;
;             PG8_LDA(At, 1, 1); PG8_STAGE(PG8_SB(1, 0), b3, voffB); PG8_STAGE(PG8_SB(1, 1), b3 + hstep, voffB); PG8_STAGE(PG8_SA(1, 0), a3, voffA);
;             PG8_WAIT_V(8); PG8_WAIT_L(0); PG8_BAR; PG8_MMA(1, 0, At, B0); PG8_MMA(1, 1, At, B1); PG8_BAR; PG8_SCHED;
;     ...
;         if constexpr (ALIGN_EPI) { if (wr == 0) PG8_BAR; }
.Ldw_532_2:
	s_waitcnt lgkmcnt(0)
	s_barrier
	s_waitcnt lgkmcnt(0)
	v_mfma_f32_16x16x32_bf16 v[118:121], v[130:133], v[176:179], v[118:121]
	v_mfma_f32_16x16x32_bf16 v[122:125], v[138:141], v[176:179], v[122:125]
	v_mfma_f32_16x16x32_bf16 v[78:81], v[130:133], v[184:187], v[78:81]
	v_mfma_f32_16x16x32_bf16 v[74:77], v[138:141], v[184:187], v[74:77]
	v_mfma_f32_16x16x32_bf16 v[58:61], v[130:133], v[192:195], v[58:61]
	v_mfma_f32_16x16x32_bf16 v[54:57], v[138:141], v[192:195], v[54:57]
	v_mfma_f32_16x16x32_bf16 v[126:129], v[130:133], v[200:203], v[126:129]
	v_mfma_f32_16x16x32_bf16 v[114:117], v[138:141], v[200:203], v[114:117]
	v_mfma_f32_16x16x32_bf16 v[118:121], v[134:137], v[180:183], v[118:121]
	v_mfma_f32_16x16x32_bf16 v[122:125], v[142:145], v[180:183], v[122:125]
	v_mfma_f32_16x16x32_bf16 v[78:81], v[134:137], v[188:191], v[78:81]
	v_mfma_f32_16x16x32_bf16 v[74:77], v[142:145], v[188:191], v[74:77]
	v_mfma_f32_16x16x32_bf16 v[58:61], v[134:137], v[196:199], v[58:61]
	v_mfma_f32_16x16x32_bf16 v[54:57], v[142:145], v[196:199], v[54:57]
	v_mfma_f32_16x16x32_bf16 v[126:129], v[134:137], v[204:207], v[126:129]
	v_mfma_f32_16x16x32_bf16 v[114:117], v[142:145], v[204:207], v[114:117]
	v_mfma_f32_16x16x32_bf16 v[110:113], v[146:149], v[176:179], v[110:113]
	v_mfma_f32_16x16x32_bf16 v[98:101], v[168:171], v[176:179], v[98:101]
	v_mfma_f32_16x16x32_bf16 v[70:73], v[146:149], v[184:187], v[70:73]
	v_mfma_f32_16x16x32_bf16 v[66:69], v[168:171], v[184:187], v[66:69]
	v_mfma_f32_16x16x32_bf16 v[42:45], v[146:149], v[192:195], v[42:45]
	v_mfma_f32_16x16x32_bf16 v[34:37], v[168:171], v[192:195], v[34:37]
	v_mfma_f32_16x16x32_bf16 v[102:105], v[146:149], v[200:203], v[102:105]
	v_mfma_f32_16x16x32_bf16 v[90:93], v[168:171], v[200:203], v[90:93]
	v_mfma_f32_16x16x32_bf16 v[110:113], v[150:153], v[180:183], v[110:113]
	v_mfma_f32_16x16x32_bf16 v[98:101], v[172:175], v[180:183], v[98:101]
	v_mfma_f32_16x16x32_bf16 v[70:73], v[150:153], v[188:191], v[70:73]
	v_mfma_f32_16x16x32_bf16 v[66:69], v[172:175], v[188:191], v[66:69]
	v_mfma_f32_16x16x32_bf16 v[42:45], v[150:153], v[196:199], v[42:45]
	v_mfma_f32_16x16x32_bf16 v[34:37], v[172:175], v[196:199], v[34:37]
	v_mfma_f32_16x16x32_bf16 v[102:105], v[150:153], v[204:207], v[102:105]
	v_mfma_f32_16x16x32_bf16 v[90:93], v[172:175], v[204:207], v[90:93]
	s_waitcnt vmcnt(8)
	s_barrier
	s_add_u32 s0, s6, 0x8000
	s_addc_u32 s1, s7, 0
	s_add_i32 s8, s86, s13
	v_lshl_add_u64 v[208:209], s[0:1], 0, v[156:157]
	s_mov_b32 m0, s8
	ds_read_b128 v[176:179], v232 offset:49152
	ds_read_b128 v[180:183], v232 offset:50176
	ds_read_b128 v[184:187], v232 offset:51200
	ds_read_b128 v[188:191], v232 offset:52224
	ds_read_b128 v[192:195], v232 offset:53248
	ds_read_b128 v[196:199], v232 offset:54272
	ds_read_b128 v[200:203], v232 offset:55296
	ds_read_b128 v[204:207], v232 offset:56320
	global_load_lds_dwordx4 v[208:209], off
	s_add_i32 m0, s8, 0x2000
	v_lshl_add_u64 v[208:209], s[0:1], 0, v[160:161]
	s_add_u32 s0, s6, 0xc000
	s_addc_u32 s1, s7, 0
	s_add_i32 s6, s87, s13
	global_load_lds_dwordx4 v[208:209], off
	v_lshl_add_u64 v[208:209], s[0:1], 0, v[156:157]
	s_mov_b32 m0, s6
	s_nop 0
	global_load_lds_dwordx4 v[208:209], off
	v_lshl_add_u64 v[208:209], s[0:1], 0, v[160:161]
	s_add_i32 m0, s6, 0x2000
	s_nop 0
	global_load_lds_dwordx4 v[208:209], off
	v_lshl_add_u64 v[208:209], s[4:5], 0, v[154:155]
	s_mov_b32 m0, s53
	s_nop 0
	global_load_lds_dwordx4 v[208:209], off
	v_lshl_add_u64 v[208:209], s[4:5], 0, v[158:159]
	s_mov_b32 m0, s55
	s_nop 0
	global_load_lds_dwordx4 v[208:209], off
	s_and_b64 vcc, exec, s[28:29]
	s_cbranch_vccnz .Ldw_532_3
	s_waitcnt vmcnt(8)
.Ldw_532_3:
	s_waitcnt lgkmcnt(0)
	s_barrier
	s_waitcnt lgkmcnt(0)
	v_mfma_f32_16x16x32_bf16 v[94:97], v[130:133], v[176:179], v[94:97]
	v_mfma_f32_16x16x32_bf16 v[106:109], v[138:141], v[176:179], v[106:109]
	v_mfma_f32_16x16x32_bf16 v[38:41], v[130:133], v[184:187], v[38:41]
	v_mfma_f32_16x16x32_bf16 v[26:29], v[138:141], v[184:187], v[26:29]
	v_mfma_f32_16x16x32_bf16 v[46:49], v[130:133], v[192:195], v[46:49]
	v_mfma_f32_16x16x32_bf16 v[62:65], v[138:141], v[192:195], v[62:65]
	v_mfma_f32_16x16x32_bf16 v[2:5], v[130:133], v[200:203], v[2:5]
	v_mfma_f32_16x16x32_bf16 v[18:21], v[138:141], v[200:203], v[18:21]
	v_mfma_f32_16x16x32_bf16 v[94:97], v[134:137], v[180:183], v[94:97]
	v_mfma_f32_16x16x32_bf16 v[106:109], v[142:145], v[180:183], v[106:109]
	v_mfma_f32_16x16x32_bf16 v[38:41], v[134:137], v[188:191], v[38:41]
	v_mfma_f32_16x16x32_bf16 v[26:29], v[142:145], v[188:191], v[26:29]
	v_mfma_f32_16x16x32_bf16 v[46:49], v[134:137], v[196:199], v[46:49]
	v_mfma_f32_16x16x32_bf16 v[62:65], v[142:145], v[196:199], v[62:65]
	v_mfma_f32_16x16x32_bf16 v[2:5], v[134:137], v[204:207], v[2:5]
	v_mfma_f32_16x16x32_bf16 v[18:21], v[142:145], v[204:207], v[18:21]
	v_mfma_f32_16x16x32_bf16 v[86:89], v[146:149], v[176:179], v[86:89]
	v_mfma_f32_16x16x32_bf16 v[82:85], v[168:171], v[176:179], v[82:85]
	v_mfma_f32_16x16x32_bf16 v[14:17], v[146:149], v[184:187], v[14:17]
	v_mfma_f32_16x16x32_bf16 v[10:13], v[168:171], v[184:187], v[10:13]
	v_mfma_f32_16x16x32_bf16 v[30:33], v[146:149], v[192:195], v[30:33]
	v_mfma_f32_16x16x32_bf16 v[50:53], v[168:171], v[192:195], v[50:53]
	v_mfma_f32_16x16x32_bf16 v[6:9], v[146:149], v[200:203], v[6:9]
	v_mfma_f32_16x16x32_bf16 v[22:25], v[168:171], v[200:203], v[22:25]
	v_mfma_f32_16x16x32_bf16 v[86:89], v[150:153], v[180:183], v[86:89]
	v_mfma_f32_16x16x32_bf16 v[82:85], v[172:175], v[180:183], v[82:85]
	v_mfma_f32_16x16x32_bf16 v[14:17], v[150:153], v[188:191], v[14:17]
	v_mfma_f32_16x16x32_bf16 v[10:13], v[172:175], v[188:191], v[10:13]
	v_mfma_f32_16x16x32_bf16 v[30:33], v[150:153], v[196:199], v[30:33]
	v_mfma_f32_16x16x32_bf16 v[50:53], v[172:175], v[196:199], v[50:53]
	v_mfma_f32_16x16x32_bf16 v[6:9], v[150:153], v[204:207], v[6:9]
	v_mfma_f32_16x16x32_bf16 v[22:25], v[172:175], v[204:207], v[22:25]
	s_waitcnt vmcnt(8)
	s_barrier
	s_add_i32 s85, s85, 2
	s_add_u32 s67, s67, 0x10000
	s_addc_u32 s84, s84, 0
	s_cmp_gt_u32 s85, 13
	s_mov_b64 s[0:1], s[2:3]
	s_cbranch_scc0 .LBB0_532
	s_and_b64 vcc, exec, s[28:29]
	s_cbranch_vccz .LBB0_535
	s_barrier

; #define PG8_STAGE(bufoff, gbase, voff) do { _Pragma("unroll") for (int _i = 0; _i < 2; ++_i) \
;         __builtin_amdgcn_global_load_lds((const unsigned*)((const char*)(gbase) + (voff)[_i]), (PG8_LAS unsigned*)(lds + (bufoff) + ldsw + _i * 8192), 16, 0, 0); } while (0)
; #define PG8_LDA(dst, b, h) do { _Pragma("unroll") for (int m = 0; m < 4; ++m) _Pragma("unroll") for (int k = 0; k < 2; ++k) dst[m][k] = *(const PG8_LAS bf16x8*)(lds + PG8_SA(b, h) + aoff + m * 2048 + k * 1024); } while (0)
; #define PG8_LDB(dst, b, h) do { _Pragma("unroll") for (int n = 0; n < 2; ++n) _Pragma("unroll") for (int k = 0; k < 2; ++k) dst[n][k] = *(const PG8_LAS bf16x8*)(lds + PG8_SB(b, h) + boff + n * 2048 + k * 1024); } while (0)
; #define PG8_MMA(ai, bj, At, Bt) do { __builtin_amdgcn_s_setprio(1); _Pragma("unroll") for (int m = 0; m < 4; ++m) _Pragma("unroll") for (int n = 0; n < 2; ++n) _Pragma("unroll") for (int k = 0; k < 2; ++k) \
;         acc[ai][bj][m][n] = __builtin_amdgcn_mfma_f32_16x16x32_bf16(Bt[n][k], At[m][k], acc[ai][bj][m][n], 0, 0, 0); __builtin_amdgcn_s_setprio(0); } while (0)
; #define PG8_WAIT_V(n) asm volatile("s_waitcnt vmcnt(" #n ")" ::: "memory")
; #define PG8_WAIT_L(n) asm volatile("s_waitcnt lgkmcnt(" #n ")" ::: "memory")
; #define PG8_BAR __builtin_amdgcn_s_barrier()
; #define PG8_SCHED __builtin_amdgcn_sched_barrier(0)
; template <class Epi, class Sched, bool ALIGN_EPI = false, bool SP2 = false>
; __device__ __forceinline__ void gemm_phase(PG8_LAS unsigned char* lds, const Gemm g, const Sched& S, const Epi& E, volatile PG8_LAS unsigned* sw = nullptr) {
;     ...
;             const char* a2 = last ? nA : cA + (size_t)(t + 2) * kstep; const char* b2 = last ? nB : cB + (size_t)(t + 2) * kstep;
;             const char* a3 = a2 + kstep; const char* b3 = b2 + kstep;
;             if (last && has_next) S.a_ready(nxt);
;             if constexpr (SP2) {
;             PG8_LDB(B0, 0, 0); PG8_LDB(B1, 0, 1); PG8_SCHED; PG8_LDA(At, 0, 0); PG8_STAGE(PG8_SA(1, 1), a1 + hstep, voffA);
;             PG8_WAIT_V(8); PG8_WAIT_L(0); PG8_BAR; PG8_MMA(0, 0, At, B0); PG8_MMA(0, 1, At, B1); PG8_BAR; PG8_SCHED;
;             PG8_LDA(At, 0, 1); PG8_STAGE(PG8_SB(0, 0), b2, voffB); PG8_STAGE(PG8_SB(0, 1), b2 + hstep, voffB); PG8_STAGE(PG8_SA(0, 0), a2, voffA);
;             PG8_WAIT_V(8); PG8_WAIT_L(0); PG8_BAR; PG8_MMA(1, 0, At, B0); PG8_MMA(1, 1, At, B1); PG8_BAR; PG8_SCHED;
.LBB0_703:
	ds_read_b128 v[128:131], v221
	ds_read_b128 v[132:135], v221 offset:1024
	ds_read_b128 v[136:139], v221 offset:2048
	ds_read_b128 v[140:143], v221 offset:3072
	ds_read_b128 v[144:147], v222
	ds_read_b128 v[148:151], v222 offset:1024
	ds_read_b128 v[152:155], v222 offset:2048
	ds_read_b128 v[156:159], v222 offset:3072
	s_add_u32 s18, s14, 0x4000
	s_addc_u32 s19, s15, 0
	s_cmp_eq_u32 s54, 40
	s_cselect_b32 s22, s6, s18
	s_cselect_b32 s23, s7, s19
	s_cselect_b32 s20, s8, s11
	s_cselect_b32 s21, s9, s13
	s_add_u32 s18, s22, 0x8000
	s_addc_u32 s19, s23, 0
	v_lshl_add_u64 v[192:193], s[14:15], 0, v[214:215]
	s_add_i32 m0, s25, 0xc000
	ds_read_b128 v[160:163], v223
	ds_read_b128 v[164:167], v223 offset:1024
	ds_read_b128 v[168:171], v223 offset:2048
	ds_read_b128 v[172:175], v223 offset:3072
	ds_read_b128 v[176:179], v223 offset:4096
	ds_read_b128 v[180:183], v223 offset:5120
	ds_read_b128 v[184:187], v223 offset:6144
	ds_read_b128 v[188:191], v223 offset:7168
	global_load_lds_dwordx4 v[192:193], off
	v_lshl_add_u64 v[192:193], s[14:15], 0, v[216:217]
	s_add_i32 m0, s25, 0xe000
	s_nop 0
	global_load_lds_dwordx4 v[192:193], off
	s_and_b64 vcc, exec, s[4:5]
	s_cbranch_vccnz .Ldw_703_0
	s_waitcnt vmcnt(8)
.Ldw_703_0:
	s_waitcnt lgkmcnt(0)
	s_barrier
	s_setprio 1
	s_waitcnt lgkmcnt(0)
	v_mfma_f32_16x16x32_bf16 v[124:127], v[128:131], v[160:163], v[124:127]
	v_mfma_f32_16x16x32_bf16 v[120:123], v[136:139], v[160:163], v[120:123]
	v_mfma_f32_16x16x32_bf16 v[116:119], v[128:131], v[168:171], v[116:119]
	v_mfma_f32_16x16x32_bf16 v[112:115], v[136:139], v[168:171], v[112:115]
	v_mfma_f32_16x16x32_bf16 v[108:111], v[128:131], v[176:179], v[108:111]
	v_mfma_f32_16x16x32_bf16 v[104:107], v[136:139], v[176:179], v[104:107]
	v_mfma_f32_16x16x32_bf16 v[100:103], v[128:131], v[184:187], v[100:103]
	v_mfma_f32_16x16x32_bf16 v[96:99], v[136:139], v[184:187], v[96:99]
	v_mfma_f32_16x16x32_bf16 v[124:127], v[132:135], v[164:167], v[124:127]
	v_mfma_f32_16x16x32_bf16 v[120:123], v[140:143], v[164:167], v[120:123]
	v_mfma_f32_16x16x32_bf16 v[116:119], v[132:135], v[172:175], v[116:119]
	v_mfma_f32_16x16x32_bf16 v[112:115], v[140:143], v[172:175], v[112:115]
	v_mfma_f32_16x16x32_bf16 v[108:111], v[132:135], v[180:183], v[108:111]
	v_mfma_f32_16x16x32_bf16 v[104:107], v[140:143], v[180:183], v[104:107]
	v_mfma_f32_16x16x32_bf16 v[100:103], v[132:135], v[188:191], v[100:103]
	v_mfma_f32_16x16x32_bf16 v[96:99], v[140:143], v[188:191], v[96:99]
	s_setprio 0
	s_setprio 1
	v_mfma_f32_16x16x32_bf16 v[68:71], v[144:147], v[160:163], v[68:71]
	v_mfma_f32_16x16x32_bf16 v[60:63], v[152:155], v[160:163], v[60:63]
	v_mfma_f32_16x16x32_bf16 v[52:55], v[144:147], v[168:171], v[52:55]
	v_mfma_f32_16x16x32_bf16 v[48:51], v[152:155], v[168:171], v[48:51]
	v_mfma_f32_16x16x32_bf16 v[44:47], v[144:147], v[176:179], v[44:47]
	v_mfma_f32_16x16x32_bf16 v[40:43], v[152:155], v[176:179], v[40:43]
	v_mfma_f32_16x16x32_bf16 v[36:39], v[144:147], v[184:187], v[36:39]
	v_mfma_f32_16x16x32_bf16 v[32:35], v[152:155], v[184:187], v[32:35]
	v_mfma_f32_16x16x32_bf16 v[68:71], v[148:151], v[164:167], v[68:71]
	v_mfma_f32_16x16x32_bf16 v[60:63], v[156:159], v[164:167], v[60:63]
	v_mfma_f32_16x16x32_bf16 v[52:55], v[148:151], v[172:175], v[52:55]
	v_mfma_f32_16x16x32_bf16 v[48:51], v[156:159], v[172:175], v[48:51]
	v_mfma_f32_16x16x32_bf16 v[44:47], v[148:151], v[180:183], v[44:47]
	v_mfma_f32_16x16x32_bf16 v[40:43], v[156:159], v[180:183], v[40:43]
	v_mfma_f32_16x16x32_bf16 v[36:39], v[148:151], v[188:191], v[36:39]
	v_mfma_f32_16x16x32_bf16 v[32:35], v[156:159], v[188:191], v[32:35]
	s_setprio 0
	s_waitcnt vmcnt(8)
	s_barrier
	s_add_i32 s55, s40, s24
	v_lshl_add_u64 v[192:193], s[20:21], 0, v[208:209]
	s_mov_b32 m0, s55
	ds_read_b128 v[160:163], v223 offset:16384
	ds_read_b128 v[164:167], v223 offset:17408
	ds_read_b128 v[168:171], v223 offset:18432
	ds_read_b128 v[172:175], v223 offset:19456
	ds_read_b128 v[176:179], v223 offset:20480
	ds_read_b128 v[180:183], v223 offset:21504
	ds_read_b128 v[184:187], v223 offset:22528
	ds_read_b128 v[188:191], v223 offset:23552
	global_load_lds_dwordx4 v[192:193], off
	s_add_i32 m0, s55, 0x2000
	s_add_u32 s56, s20, 0x4000
	v_lshl_add_u64 v[192:193], s[20:21], 0, v[204:205]
	s_addc_u32 s57, s21, 0
	s_add_i32 s55, s41, s24
	global_load_lds_dwordx4 v[192:193], off
	v_lshl_add_u64 v[192:193], s[56:57], 0, v[208:209]
	s_mov_b32 m0, s55
	s_nop 0
	global_load_lds_dwordx4 v[192:193], off
	v_lshl_add_u64 v[192:193], s[56:57], 0, v[204:205]
	s_add_i32 m0, s55, 0x2000
	s_nop 0
	global_load_lds_dwordx4 v[192:193], off
	v_lshl_add_u64 v[192:193], s[22:23], 0, v[210:211]
	s_mov_b32 m0, s25
	s_nop 0
	global_load_lds_dwordx4 v[192:193], off
	v_lshl_add_u64 v[192:193], s[22:23], 0, v[206:207]
	s_mov_b32 m0, s26
	s_nop 0
	global_load_lds_dwordx4 v[192:193], off
	s_and_b64 vcc, exec, s[4:5]
	s_cbranch_vccnz .Ldw_703_1
	s_waitcnt vmcnt(8)
; #define PG8_STAGE(bufoff, gbase, voff) do { _Pragma("unroll") for (int _i = 0; _i < 2; ++_i) \
;         __builtin_amdgcn_global_load_lds((const unsigned*)((const char*)(gbase) + (voff)[_i]), (PG8_LAS unsigned*)(lds + (bufoff) + ldsw + _i * 8192), 16, 0, 0); } while (0)
; #define PG8_LDA(dst, b, h) do { _Pragma("unroll") for (int m = 0; m < 4; ++m) _Pragma("unroll") for (int k = 0; k < 2; ++k) dst[m][k] = *(const PG8_LAS bf16x8*)(lds + PG8_SA(b, h) + aoff + m * 2048 + k * 1024); } while (0)
; #define PG8_LDB(dst, b, h) do { _Pragma("unroll") for (int n = 0; n < 2; ++n) _Pragma("unroll") for (int k = 0; k < 2; ++k) dst[n][k] = *(const PG8_LAS bf16x8*)(lds + PG8_SB(b, h) + boff + n * 2048 + k * 1024); } while (0)
; #define PG8_MMA(ai, bj, At, Bt) do { __builtin_amdgcn_s_setprio(1); _Pragma("unroll") for (int m = 0; m < 4; ++m) _Pragma("unroll") for (int n = 0; n < 2; ++n) _Pragma("unroll") for (int k = 0; k < 2; ++k) \
;         acc[ai][bj][m][n] = __builtin_amdgcn_mfma_f32_16x16x32_bf16(Bt[n][k], At[m][k], acc[ai][bj][m][n], 0, 0, 0); __builtin_amdgcn_s_setprio(0); } while (0)
; #define PG8_WAIT_V(n) asm volatile("s_waitcnt vmcnt(" #n ")" ::: "memory")
; #define PG8_WAIT_L(n) asm volatile("s_waitcnt lgkmcnt(" #n ")" ::: "memory")
; #define PG8_BAR __builtin_amdgcn_s_barrier()
; #define PG8_SCHED __builtin_amdgcn_sched_barrier(0)
; template <class Epi, class Sched, bool ALIGN_EPI = false, bool SP2 = false>
; __device__ __forceinline__ void gemm_phase(PG8_LAS unsigned char* lds, const Gemm g, const Sched& S, const Epi& E, volatile PG8_LAS unsigned* sw = nullptr) {
;     ...
;             PG8_WAIT_V(8); PG8_WAIT_L(0); PG8_BAR; PG8_MMA(1, 0, At, B0); PG8_MMA(1, 1, At, B1); PG8_BAR; PG8_SCHED;
;             PG8_LDB(B0, 1, 0); PG8_LDB(B1, 1, 1); PG8_SCHED; PG8_LDA(At, 1, 0); PG8_STAGE(PG8_SA(0, 1), a2 + hstep, voffA);
;             PG8_WAIT_V(8); PG8_WAIT_L(0); PG8_BAR; PG8_MMA(0, 0, At, B0); PG8_MMA(0, 1, At, B1); PG8_BAR; PG8_SCHED;
.Ldw_703_1:
	s_waitcnt lgkmcnt(0)
	s_barrier
	s_setprio 1
	s_waitcnt lgkmcnt(0)
	v_mfma_f32_16x16x32_bf16 v[92:95], v[128:131], v[160:163], v[92:95]
	v_mfma_f32_16x16x32_bf16 v[88:91], v[136:139], v[160:163], v[88:91]
	v_mfma_f32_16x16x32_bf16 v[84:87], v[128:131], v[168:171], v[84:87]
	v_mfma_f32_16x16x32_bf16 v[80:83], v[136:139], v[168:171], v[80:83]
	v_mfma_f32_16x16x32_bf16 v[76:79], v[128:131], v[176:179], v[76:79]
	v_mfma_f32_16x16x32_bf16 v[72:75], v[136:139], v[176:179], v[72:75]
	v_mfma_f32_16x16x32_bf16 v[64:67], v[128:131], v[184:187], v[64:67]
	v_mfma_f32_16x16x32_bf16 v[56:59], v[136:139], v[184:187], v[56:59]
	v_mfma_f32_16x16x32_bf16 v[92:95], v[132:135], v[164:167], v[92:95]
	v_mfma_f32_16x16x32_bf16 v[88:91], v[140:143], v[164:167], v[88:91]
	v_mfma_f32_16x16x32_bf16 v[84:87], v[132:135], v[172:175], v[84:87]
	v_mfma_f32_16x16x32_bf16 v[80:83], v[140:143], v[172:175], v[80:83]
	v_mfma_f32_16x16x32_bf16 v[76:79], v[132:135], v[180:183], v[76:79]
	v_mfma_f32_16x16x32_bf16 v[72:75], v[140:143], v[180:183], v[72:75]
	v_mfma_f32_16x16x32_bf16 v[64:67], v[132:135], v[188:191], v[64:67]
	v_mfma_f32_16x16x32_bf16 v[56:59], v[140:143], v[188:191], v[56:59]
	s_setprio 0
	s_setprio 1
	v_mfma_f32_16x16x32_bf16 v[28:31], v[144:147], v[160:163], v[28:31]
	v_mfma_f32_16x16x32_bf16 v[24:27], v[152:155], v[160:163], v[24:27]
	v_mfma_f32_16x16x32_bf16 v[20:23], v[144:147], v[168:171], v[20:23]
	v_mfma_f32_16x16x32_bf16 v[16:19], v[152:155], v[168:171], v[16:19]
	v_mfma_f32_16x16x32_bf16 v[12:15], v[144:147], v[176:179], v[12:15]
	v_mfma_f32_16x16x32_bf16 v[8:11], v[152:155], v[176:179], v[8:11]
	v_mfma_f32_16x16x32_bf16 v[4:7], v[144:147], v[184:187], v[4:7]
	v_mfma_f32_16x16x32_bf16 v[0:3], v[152:155], v[184:187], v[0:3]
	v_mfma_f32_16x16x32_bf16 v[28:31], v[148:151], v[164:167], v[28:31]
	v_mfma_f32_16x16x32_bf16 v[24:27], v[156:159], v[164:167], v[24:27]
	v_mfma_f32_16x16x32_bf16 v[20:23], v[148:151], v[172:175], v[20:23]
	v_mfma_f32_16x16x32_bf16 v[16:19], v[156:159], v[172:175], v[16:19]
	v_mfma_f32_16x16x32_bf16 v[12:15], v[148:151], v[180:183], v[12:15]
	v_mfma_f32_16x16x32_bf16 v[8:11], v[156:159], v[180:183], v[8:11]
	v_mfma_f32_16x16x32_bf16 v[4:7], v[148:151], v[188:191], v[4:7]
	v_mfma_f32_16x16x32_bf16 v[0:3], v[156:159], v[188:191], v[0:3]
	s_setprio 0
	s_waitcnt vmcnt(8)
	s_barrier
	s_add_i32 s55, 0, 0x18000
	s_add_i32 s56, 0, 0x1c000
	v_add_u32_e32 v140, s55, v220
	v_add_u32_e32 v156, s56, v220
	ds_read_b128 v[128:131], v140
	ds_read_b128 v[132:135], v140 offset:1024
	ds_read_b128 v[136:139], v140 offset:2048
	ds_read_b128 v[140:143], v140 offset:3072
	ds_read_b128 v[144:147], v156
	ds_read_b128 v[148:151], v156 offset:1024
	ds_read_b128 v[152:155], v156 offset:2048
	ds_read_b128 v[156:159], v156 offset:3072
	s_add_u32 s22, s22, 0x4000
	s_addc_u32 s23, s23, 0
	s_mov_b32 m0, s27
	v_lshl_add_u64 v[192:193], s[22:23], 0, v[210:211]
	ds_read_b128 v[160:163], v223 offset:32768
	ds_read_b128 v[164:167], v223 offset:33792
	ds_read_b128 v[168:171], v223 offset:34816
	ds_read_b128 v[172:175], v223 offset:35840
	ds_read_b128 v[176:179], v223 offset:36864
	ds_read_b128 v[180:183], v223 offset:37888
	ds_read_b128 v[184:187], v223 offset:38912
	ds_read_b128 v[188:191], v223 offset:39936
	global_load_lds_dwordx4 v[192:193], off
	v_lshl_add_u64 v[192:193], s[22:23], 0, v[206:207]
	s_mov_b32 m0, s28
	s_nop 0
	global_load_lds_dwordx4 v[192:193], off
	s_and_b64 vcc, exec, s[4:5]
	s_cbranch_vccnz .Ldw_703_2
	s_waitcnt vmcnt(8)
; #define PG8_STAGE(bufoff, gbase, voff) do { _Pragma("unroll") for (int _i = 0; _i < 2; ++_i) \
;         __builtin_amdgcn_global_load_lds((const unsigned*)((const char*)(gbase) + (voff)[_i]), (PG8_LAS unsigned*)(lds + (bufoff) + ldsw + _i * 8192), 16, 0, 0); } while (0)
; #define PG8_LDA(dst, b, h) do { _Pragma("unroll") for (int m = 0; m < 4; ++m) _Pragma("unroll") for (int k = 0; k < 2; ++k) dst[m][k] = *(const PG8_LAS bf16x8*)(lds + PG8_SA(b, h) + aoff + m * 2048 + k * 1024); } while (0)
; #define PG8_MMA(ai, bj, At, Bt) do { __builtin_amdgcn_s_setprio(1); _Pragma("unroll") for (int m = 0; m < 4; ++m) _Pragma("unroll") for (int n = 0; n < 2; ++n) _Pragma("unroll") for (int k = 0; k < 2; ++k) \
;         acc[ai][bj][m][n] = __builtin_amdgcn_mfma_f32_16x16x32_bf16(Bt[n][k], At[m][k], acc[ai][bj][m][n], 0, 0, 0); __builtin_amdgcn_s_setprio(0); } while (0)
; #define PG8_WAIT_V(n) asm volatile("s_waitcnt vmcnt(" #n ")" ::: "memory")
; #define PG8_WAIT_L(n) asm volatile("s_waitcnt lgkmcnt(" #n ")" ::: "memory")
; #define PG8_BAR __builtin_amdgcn_s_barrier()
; #define PG8_SCHED __builtin_amdgcn_sched_barrier(0)
; template <class Epi, class Sched, bool ALIGN_EPI = false, bool SP2 = false>
; __device__ __forceinline__ void gemm_phase(PG8_LAS unsigned char* lds, const Gemm g, const Sched& S, const Epi& E, volatile PG8_LAS unsigned* sw = nullptr) {
;     ...
;             PG8_WAIT_V(8); PG8_WAIT_L(0); PG8_BAR; PG8_MMA(0, 0, At, B0); PG8_MMA(0, 1, At, B1); PG8_BAR; PG8_SCHED;
;             PG8_LDA(At, 1, 1); PG8_STAGE(PG8_SB(1, 0), b3, voffB); PG8_STAGE(PG8_SB(1, 1), b3 + hstep, voffB); PG8_STAGE(PG8_SA(1, 0), a3, voffA);
;             PG8_WAIT_V(8); PG8_WAIT_L(0); PG8_BAR; PG8_MMA(1, 0, At, B0); PG8_MMA(1, 1, At, B1); PG8_BAR; PG8_SCHED;
;     ...
;         if constexpr (ALIGN_EPI) { if (wr == 0) PG8_BAR; }
.Ldw_703_2:
	s_waitcnt lgkmcnt(0)
	s_barrier
	s_setprio 1
	s_waitcnt lgkmcnt(0)
	v_mfma_f32_16x16x32_bf16 v[124:127], v[128:131], v[160:163], v[124:127]
	v_mfma_f32_16x16x32_bf16 v[120:123], v[136:139], v[160:163], v[120:123]
	v_mfma_f32_16x16x32_bf16 v[116:119], v[128:131], v[168:171], v[116:119]
	v_mfma_f32_16x16x32_bf16 v[112:115], v[136:139], v[168:171], v[112:115]
	v_mfma_f32_16x16x32_bf16 v[108:111], v[128:131], v[176:179], v[108:111]
	v_mfma_f32_16x16x32_bf16 v[104:107], v[136:139], v[176:179], v[104:107]
	v_mfma_f32_16x16x32_bf16 v[100:103], v[128:131], v[184:187], v[100:103]
	v_mfma_f32_16x16x32_bf16 v[96:99], v[136:139], v[184:187], v[96:99]
	v_mfma_f32_16x16x32_bf16 v[124:127], v[132:135], v[164:167], v[124:127]
	v_mfma_f32_16x16x32_bf16 v[120:123], v[140:143], v[164:167], v[120:123]
	v_mfma_f32_16x16x32_bf16 v[116:119], v[132:135], v[172:175], v[116:119]
	v_mfma_f32_16x16x32_bf16 v[112:115], v[140:143], v[172:175], v[112:115]
	v_mfma_f32_16x16x32_bf16 v[108:111], v[132:135], v[180:183], v[108:111]
	v_mfma_f32_16x16x32_bf16 v[104:107], v[140:143], v[180:183], v[104:107]
	v_mfma_f32_16x16x32_bf16 v[100:103], v[132:135], v[188:191], v[100:103]
	v_mfma_f32_16x16x32_bf16 v[96:99], v[140:143], v[188:191], v[96:99]
	s_setprio 0
	s_setprio 1
	v_mfma_f32_16x16x32_bf16 v[68:71], v[144:147], v[160:163], v[68:71]
	v_mfma_f32_16x16x32_bf16 v[60:63], v[152:155], v[160:163], v[60:63]
	v_mfma_f32_16x16x32_bf16 v[52:55], v[144:147], v[168:171], v[52:55]
	v_mfma_f32_16x16x32_bf16 v[48:51], v[152:155], v[168:171], v[48:51]
	v_mfma_f32_16x16x32_bf16 v[44:47], v[144:147], v[176:179], v[44:47]
	v_mfma_f32_16x16x32_bf16 v[40:43], v[152:155], v[176:179], v[40:43]
	v_mfma_f32_16x16x32_bf16 v[36:39], v[144:147], v[184:187], v[36:39]
	v_mfma_f32_16x16x32_bf16 v[32:35], v[152:155], v[184:187], v[32:35]
	v_mfma_f32_16x16x32_bf16 v[68:71], v[148:151], v[164:167], v[68:71]
	v_mfma_f32_16x16x32_bf16 v[60:63], v[156:159], v[164:167], v[60:63]
	v_mfma_f32_16x16x32_bf16 v[52:55], v[148:151], v[172:175], v[52:55]
	v_mfma_f32_16x16x32_bf16 v[48:51], v[156:159], v[172:175], v[48:51]
	v_mfma_f32_16x16x32_bf16 v[44:47], v[148:151], v[180:183], v[44:47]
	v_mfma_f32_16x16x32_bf16 v[40:43], v[156:159], v[180:183], v[40:43]
	v_mfma_f32_16x16x32_bf16 v[36:39], v[148:151], v[188:191], v[36:39]
	v_mfma_f32_16x16x32_bf16 v[32:35], v[156:159], v[188:191], v[32:35]
	s_setprio 0
	s_waitcnt vmcnt(8)
	s_barrier
	s_add_u32 s22, s20, 0x8000
	s_addc_u32 s23, s21, 0
	s_add_i32 s55, s55, s24
	v_lshl_add_u64 v[192:193], s[22:23], 0, v[208:209]
	s_mov_b32 m0, s55
	ds_read_b128 v[160:163], v223 offset:49152
	ds_read_b128 v[164:167], v223 offset:50176
	ds_read_b128 v[168:171], v223 offset:51200
	ds_read_b128 v[172:175], v223 offset:52224
	ds_read_b128 v[176:179], v223 offset:53248
	ds_read_b128 v[180:183], v223 offset:54272
	ds_read_b128 v[184:187], v223 offset:55296
	ds_read_b128 v[188:191], v223 offset:56320
	global_load_lds_dwordx4 v[192:193], off
	s_add_i32 m0, s55, 0x2000
	s_add_u32 s20, s20, 0xc000
	v_lshl_add_u64 v[192:193], s[22:23], 0, v[204:205]
	s_addc_u32 s21, s21, 0
	s_add_i32 s22, s56, s24
	global_load_lds_dwordx4 v[192:193], off
	v_lshl_add_u64 v[192:193], s[20:21], 0, v[208:209]
	s_mov_b32 m0, s22
	s_nop 0
	global_load_lds_dwordx4 v[192:193], off
	v_lshl_add_u64 v[192:193], s[20:21], 0, v[204:205]
	s_add_i32 m0, s22, 0x2000
	s_nop 0
	global_load_lds_dwordx4 v[192:193], off
	v_lshl_add_u64 v[192:193], s[18:19], 0, v[210:211]
	s_mov_b32 m0, s34
	s_nop 0
	global_load_lds_dwordx4 v[192:193], off
	v_lshl_add_u64 v[192:193], s[18:19], 0, v[206:207]
	s_mov_b32 m0, s35
	s_nop 0
	global_load_lds_dwordx4 v[192:193], off
	s_and_b64 vcc, exec, s[4:5]
	s_cbranch_vccnz .Ldw_703_3
	s_waitcnt vmcnt(8)
.Ldw_703_3:
	s_waitcnt lgkmcnt(0)
	s_barrier
	s_setprio 1
	s_waitcnt lgkmcnt(0)
	v_mfma_f32_16x16x32_bf16 v[92:95], v[128:131], v[160:163], v[92:95]
	v_mfma_f32_16x16x32_bf16 v[88:91], v[136:139], v[160:163], v[88:91]
	v_mfma_f32_16x16x32_bf16 v[84:87], v[128:131], v[168:171], v[84:87]
	v_mfma_f32_16x16x32_bf16 v[80:83], v[136:139], v[168:171], v[80:83]
	v_mfma_f32_16x16x32_bf16 v[76:79], v[128:131], v[176:179], v[76:79]
	v_mfma_f32_16x16x32_bf16 v[72:75], v[136:139], v[176:179], v[72:75]
	v_mfma_f32_16x16x32_bf16 v[64:67], v[128:131], v[184:187], v[64:67]
	v_mfma_f32_16x16x32_bf16 v[56:59], v[136:139], v[184:187], v[56:59]
	v_mfma_f32_16x16x32_bf16 v[92:95], v[132:135], v[164:167], v[92:95]
	v_mfma_f32_16x16x32_bf16 v[88:91], v[140:143], v[164:167], v[88:91]
	v_mfma_f32_16x16x32_bf16 v[84:87], v[132:135], v[172:175], v[84:87]
	v_mfma_f32_16x16x32_bf16 v[80:83], v[140:143], v[172:175], v[80:83]
	v_mfma_f32_16x16x32_bf16 v[76:79], v[132:135], v[180:183], v[76:79]
	v_mfma_f32_16x16x32_bf16 v[72:75], v[140:143], v[180:183], v[72:75]
	v_mfma_f32_16x16x32_bf16 v[64:67], v[132:135], v[188:191], v[64:67]
	v_mfma_f32_16x16x32_bf16 v[56:59], v[140:143], v[188:191], v[56:59]
	s_setprio 0
	s_setprio 1
	v_mfma_f32_16x16x32_bf16 v[28:31], v[144:147], v[160:163], v[28:31]
	v_mfma_f32_16x16x32_bf16 v[24:27], v[152:155], v[160:163], v[24:27]
	v_mfma_f32_16x16x32_bf16 v[20:23], v[144:147], v[168:171], v[20:23]
	v_mfma_f32_16x16x32_bf16 v[16:19], v[152:155], v[168:171], v[16:19]
	v_mfma_f32_16x16x32_bf16 v[12:15], v[144:147], v[176:179], v[12:15]
	v_mfma_f32_16x16x32_bf16 v[8:11], v[152:155], v[176:179], v[8:11]
	v_mfma_f32_16x16x32_bf16 v[4:7], v[144:147], v[184:187], v[4:7]
	v_mfma_f32_16x16x32_bf16 v[0:3], v[152:155], v[184:187], v[0:3]
	v_mfma_f32_16x16x32_bf16 v[28:31], v[148:151], v[164:167], v[28:31]
	v_mfma_f32_16x16x32_bf16 v[24:27], v[156:159], v[164:167], v[24:27]
	v_mfma_f32_16x16x32_bf16 v[20:23], v[148:151], v[172:175], v[20:23]
	v_mfma_f32_16x16x32_bf16 v[16:19], v[156:159], v[172:175], v[16:19]
	v_mfma_f32_16x16x32_bf16 v[12:15], v[148:151], v[180:183], v[12:15]
	v_mfma_f32_16x16x32_bf16 v[8:11], v[156:159], v[180:183], v[8:11]
	v_mfma_f32_16x16x32_bf16 v[4:7], v[148:151], v[188:191], v[4:7]
	v_mfma_f32_16x16x32_bf16 v[0:3], v[156:159], v[188:191], v[0:3]
	s_setprio 0
	s_waitcnt vmcnt(8)
	s_barrier
	s_add_i32 s54, s54, 2
	s_add_u32 s14, s14, 0x10000
	s_addc_u32 s15, s15, 0
	s_add_u32 s11, s11, 0x10000
	s_addc_u32 s13, s13, 0
	s_cmp_gt_u32 s54, 41
	s_cbranch_scc0 .LBB0_703
	s_and_b64 vcc, exec, s[4:5]
	s_cbranch_vccz .LBB0_706
	s_barrier
